# speedup vs baseline: 1.0130x; 1.0025x over previous
; DI unsigned pk2(float lo, float hi) { const f32x2 v = {lo, hi}; return __builtin_bit_cast(unsigned, __builtin_convertvector(v, bf16x2_t)); }
; DI float bflo(unsigned w) { return __uint_as_float(w << 16); }
; DI float bfhi(unsigned w) { return __uint_as_float(w & 0xffff0000u); }
; DI float wave_sum(float v) {
; #pragma unroll
;     for (int o = 1; o < 64; o <<= 1) v += __shfl_xor(v, o);
;     return v;
; }
; DI void ln_rows(const float* __restrict__ xres, const bf16_t* __restrict__ xres_b, const bf16_t* __restrict__ mb, float* __restrict__ x1f, bf16_t* __restrict__ xb, const float* __restrict__ g, const float* __restrict__ bta) {
;     ...
;     for (int r = gw; r < T_TOK; r += nw) {
;         const float* xr = xres + (size_t)r * DM + 4 * lane;
;         const bf16_t* mr = mb + (size_t)r * DM + 4 * lane;
;         f32x4 v[4]; float s = 0.f;
; #pragma unroll
;         for (int j = 0; j < 4; ++j) {
;             f32x4 xv; if (xres_b) { const u32x2 xw_ = *(const u32x2*)(xres_b + (size_t)r * DM + 4 * lane + 256 * j); xv = (f32x4){bflo(xw_.x), bfhi(xw_.x), bflo(xw_.y), bfhi(xw_.y)}; } else xv = *(const f32x4*)(xr + 256 * j);
;             const u32x2 mv = *(const u32x2*)(mr + 256 * j);
;             v[j].x = ALPHA * xv.x + bflo(mv.x); v[j].y = ALPHA * xv.y + bfhi(mv.x); v[j].z = ALPHA * xv.z + bflo(mv.y); v[j].w = ALPHA * xv.w + bfhi(mv.y);
;             s += (v[j].x + v[j].y) + (v[j].z + v[j].w);
;         }
;         const float mean = wave_sum(s) * (1.f / DM); float q = 0.f;
; #pragma unroll
;         for (int j = 0; j < 4; ++j) { v[j] = v[j] - mean; q += (v[j].x * v[j].x + v[j].y * v[j].y) + (v[j].z * v[j].z + v[j].w * v[j].w); }
;         const float rstd = rsqrtf(wave_sum(q) * (1.f / DM) + LN_EPS);
; #pragma unroll
;         for (int j = 0; j < 4; ++j) {
;             const f32x4 o = v[j] * rstd * g4[j] + b4[j];
;             u32x2 wv; wv.x = pk2(o.x, o.y); wv.y = pk2(o.z, o.w);
;             *(u32x2*)(xb + (size_t)r * PA + 4 * lane + 256 * j) = wv;
;         }
;     }
.LBB0_111:
	s_waitcnt vmcnt(0)
	v_lshlrev_b32_e32 v52, 16, v54
	v_and_b32_e32 v53, 0xffff0000, v54
	v_pk_fma_f32 v[52:53], v[36:37], s[78:79], v[52:53] op_sel_hi:[1,0,1]
	v_lshlrev_b32_e32 v36, 16, v55
	v_and_b32_e32 v37, 0xffff0000, v55
	v_pk_fma_f32 v[54:55], v[38:39], s[78:79], v[36:37] op_sel_hi:[1,0,1]
	v_add_f32_e32 v37, v52, v53
	v_add_f32_e32 v36, v54, v55
	v_add_f32_e32 v36, v37, v36
	v_add_f32_e32 v66, 0, v36
	v_lshlrev_b32_e32 v36, 16, v56
	v_and_b32_e32 v37, 0xffff0000, v56
	v_lshlrev_b32_e32 v38, 16, v57
	v_and_b32_e32 v39, 0xffff0000, v57
	v_pk_fma_f32 v[36:37], v[40:41], s[78:79], v[36:37] op_sel_hi:[1,0,1]
	v_pk_fma_f32 v[38:39], v[42:43], s[78:79], v[38:39] op_sel_hi:[1,0,1]
	v_add_f32_e32 v41, v36, v37
	v_add_f32_e32 v40, v38, v39
	v_add_f32_e32 v40, v41, v40
	v_add_f32_e32 v56, v66, v40
	v_lshlrev_b32_e32 v40, 16, v58
	v_and_b32_e32 v41, 0xffff0000, v58
	v_lshlrev_b32_e32 v42, 16, v59
	v_and_b32_e32 v43, 0xffff0000, v59
	v_pk_fma_f32 v[40:41], v[44:45], s[78:79], v[40:41] op_sel_hi:[1,0,1]
	v_pk_fma_f32 v[42:43], v[46:47], s[78:79], v[42:43] op_sel_hi:[1,0,1]
	v_add_f32_e32 v45, v40, v41
	v_add_f32_e32 v44, v42, v43
	v_add_f32_e32 v44, v45, v44
	s_mov_b32 s0, 0x4b01000
	v_add_f32_e32 v56, v56, v44
	v_add_co_u32_e32 v44, vcc, s0, v50
	s_mov_b32 s0, 0xdb01000
	s_nop 0
	v_addc_co_u32_e32 v45, vcc, 0, v51, vcc
	global_load_dwordx2 v[44:45], v[44:45], off offset:1536
	s_add_i32 s2, s2, s90
	s_add_u32 s4, s4, s74
	s_addc_u32 s5, s5, s75
	s_add_u32 s6, s6, s74
	s_addc_u32 s7, s7, s75
	v_lshl_add_u64 v[48:49], v[48:49], 0, s[10:11]
	s_cmpk_gt_i32 s2, 0x7fff
	s_waitcnt vmcnt(0)
	v_lshlrev_b32_e32 v46, 16, v44
	v_and_b32_e32 v47, 0xffff0000, v44
	v_lshlrev_b32_e32 v44, 16, v45
	v_and_b32_e32 v45, 0xffff0000, v45
	v_pk_fma_f32 v[32:33], v[32:33], s[78:79], v[46:47] op_sel_hi:[1,0,1]
	v_pk_fma_f32 v[34:35], v[34:35], s[78:79], v[44:45] op_sel_hi:[1,0,1]
	v_mov_b32_e32 v44, v32
	v_mov_b32_e32 v45, v34
	v_mov_b32_e32 v46, v33
	v_mov_b32_e32 v47, v35
	v_pk_add_f32 v[44:45], v[44:45], v[46:47]
	s_nop 0
	v_add_f32_e32 v44, v44, v45
	v_add_f32_e32 v44, v56, v44
	s_waitcnt lgkmcnt(0)
	s_nop 1
	v_add_f32_dpp v44, v44, v44 quad_perm:[1,0,3,2] row_mask:0xf bank_mask:0xf
	s_nop 1
	v_add_f32_dpp v44, v44, v44 quad_perm:[2,3,0,1] row_mask:0xf bank_mask:0xf
	s_nop 1
	v_add_f32_dpp v44, v44, v44 row_half_mirror row_mask:0xf bank_mask:0xf
	s_nop 1
	v_add_f32_dpp v44, v44, v44 row_mirror row_mask:0xf bank_mask:0xf
	s_nop 1
	v_add_f32_dpp v44, v44, v44 row_bcast:15 row_mask:0xa bank_mask:0xf
	s_nop 1
	v_add_f32_dpp v44, v44, v44 row_bcast:31 row_mask:0xc bank_mask:0xf
	s_nop 0
	v_readlane_b32 vcc_lo, v44, 63
	s_nop 1
	v_mov_b32_e32 v66, vcc_lo
	v_fmamk_f32 v53, v66, 0xba800000, v53
	v_fmac_f32_e32 v52, 0xba800000, v66
	v_fmamk_f32 v55, v66, 0xba800000, v55
	v_fmac_f32_e32 v54, 0xba800000, v66
	v_pk_mul_f32 v[44:45], v[54:55], v[54:55]
	v_pk_mul_f32 v[46:47], v[52:53], v[52:53]
	v_fmamk_f32 v37, v66, 0xba800000, v37
	v_pk_mov_b32 v[56:57], v[46:47], v[44:45] op_sel:[1,0]
	v_mov_b32_e32 v47, v45
	v_pk_add_f32 v[44:45], v[56:57], v[46:47]
	v_fmac_f32_e32 v36, 0xba800000, v66
	v_fmamk_f32 v39, v66, 0xba800000, v39
	v_fmac_f32_e32 v38, 0xba800000, v66
	v_pk_add_f32 v[44:45], v[44:45], v[44:45] op_sel_hi:[0,1]
	v_pk_mul_f32 v[46:47], v[38:39], v[38:39]
	v_pk_mul_f32 v[56:57], v[36:37], v[36:37]
	v_fmac_f32_e32 v40, 0xba800000, v66
	v_pk_mov_b32 v[58:59], v[56:57], v[46:47] op_sel:[1,0]
	v_mov_b32_e32 v57, v47
	v_fmamk_f32 v41, v66, 0xba800000, v41
	v_fmac_f32_e32 v42, 0xba800000, v66
	v_mul_f32_e32 v44, v40, v40
	v_pk_add_f32 v[46:47], v[58:59], v[56:57]
	v_fmamk_f32 v43, v66, 0xba800000, v43
	v_pk_fma_f32 v[56:57], v[40:41], v[40:41], v[44:45] op_sel_hi:[1,1,0]
	v_mul_f32_e32 v44, v42, v42
	v_pk_add_f32 v[46:47], v[46:47], v[46:47] op_sel_hi:[0,1]
	v_pk_fma_f32 v[58:59], v[42:43], v[42:43], v[44:45] op_sel_hi:[1,1,0]
	v_fmamk_f32 v35, v66, 0xba800000, v35
	v_fmac_f32_e32 v34, 0xba800000, v66
	v_fmamk_f32 v33, v66, 0xba800000, v33
	v_fmac_f32_e32 v32, 0xba800000, v66
	v_mul_f32_e32 v56, v32, v32
	v_mul_f32_e32 v58, v33, v33
	v_mul_f32_e32 v44, v34, v34
	v_mul_f32_e32 v46, v35, v35
	v_pk_add_f32 v[56:57], v[56:57], v[58:59]
	v_pk_add_f32 v[44:45], v[44:45], v[46:47]
	s_nop 0
	v_pk_add_f32 v[44:45], v[56:57], v[44:45]
	s_nop 0
	v_add_f32_e32 v44, v44, v45
	s_waitcnt lgkmcnt(0)
	s_nop 1
	v_add_f32_dpp v44, v44, v44 quad_perm:[1,0,3,2] row_mask:0xf bank_mask:0xf
	s_nop 1
	v_add_f32_dpp v44, v44, v44 quad_perm:[2,3,0,1] row_mask:0xf bank_mask:0xf
	s_nop 1
	v_add_f32_dpp v44, v44, v44 row_half_mirror row_mask:0xf bank_mask:0xf
	s_nop 1
	v_add_f32_dpp v44, v44, v44 row_mirror row_mask:0xf bank_mask:0xf
	s_nop 1
	v_add_f32_dpp v44, v44, v44 row_bcast:15 row_mask:0xa bank_mask:0xf
	s_nop 1
	v_add_f32_dpp v44, v44, v44 row_bcast:31 row_mask:0xc bank_mask:0xf
	s_nop 0
	v_readlane_b32 vcc_lo, v44, 63
	s_nop 1
	v_mov_b32_e32 v44, vcc_lo
	v_fmamk_f32 v44, v44, 0x3a800000, v195
	v_cmp_gt_f32_e32 vcc, s69, v44
	v_mul_f32_e32 v45, 0x4b800000, v44
	s_nop 0
	v_cndmask_b32_e32 v44, v44, v45, vcc
	v_rsq_f32_e32 v44, v44
	s_nop 0
	v_mul_f32_e32 v45, 0x45800000, v44
	v_cndmask_b32_e32 v44, v44, v45, vcc
	v_pk_mul_f32 v[36:37], v[36:37], v[44:45] op_sel_hi:[1,0]
	v_pk_mul_f32 v[38:39], v[38:39], v[44:45] op_sel_hi:[1,0]
	v_add_co_u32_e32 v50, vcc, s0, v50
	v_pk_fma_f32 v[38:39], v[6:7], v[38:39], v[14:15]
	v_pk_fma_f32 v[36:37], v[4:5], v[36:37], v[12:13]
	v_addc_co_u32_e32 v51, vcc, 0, v51, vcc
	v_cvt_pk_bf16_f32 v36, v36, v37
	v_cvt_pk_bf16_f32 v37, v38, v39
	v_pk_mul_f32 v[46:47], v[52:53], v[44:45] op_sel_hi:[1,0]
	v_pk_mul_f32 v[52:53], v[54:55], v[44:45] op_sel_hi:[1,0]
	global_store_dwordx2 v[50:51], v[36:37], off offset:512
	v_pk_mul_f32 v[36:37], v[40:41], v[44:45] op_sel_hi:[1,0]
	v_pk_mul_f32 v[38:39], v[42:43], v[44:45] op_sel_hi:[1,0]
	v_pk_mul_f32 v[32:33], v[32:33], v[44:45] op_sel_hi:[1,0]
	v_pk_mul_f32 v[34:35], v[34:35], v[44:45] op_sel_hi:[1,0]
	v_pk_fma_f32 v[52:53], v[2:3], v[52:53], v[10:11]
	v_pk_fma_f32 v[46:47], v[0:1], v[46:47], v[8:9]
	v_pk_fma_f32 v[38:39], v[18:19], v[38:39], v[26:27]
	v_pk_fma_f32 v[36:37], v[16:17], v[36:37], v[24:25]
	v_pk_fma_f32 v[34:35], v[22:23], v[34:35], v[30:31]
	v_pk_fma_f32 v[32:33], v[20:21], v[32:33], v[28:29]
	v_cvt_pk_bf16_f32 v46, v46, v47
	v_cvt_pk_bf16_f32 v47, v52, v53
	v_cvt_pk_bf16_f32 v36, v36, v37
	v_cvt_pk_bf16_f32 v37, v38, v39
	v_cvt_pk_bf16_f32 v32, v32, v33
	v_cvt_pk_bf16_f32 v33, v34, v35
	global_store_dwordx2 v[50:51], v[46:47], off
	global_store_dwordx2 v[50:51], v[36:37], off offset:1024
	global_store_dwordx2 v[50:51], v[32:33], off offset:1536
	s_cbranch_scc1 .LBB0_128

; DI void mixer_tile(unsigned char* smem_, const Params& p, int layer, const bf16_t* __restrict__ proj, bf16_t* __restrict__ y, int tile_) {
;     ...
;         float w[31];
;         const float* cw = p.in[2] + (size_t)layer * 31 * 256;
; #pragma unroll
;         for (int k = 0; k < 31; ++k) w[k] = cw[k * 256 + tid];
;         const float bias = p.in[3][layer * 256 + tid];
;         float u[62];
; #pragma unroll
;         for (int r = 0; r < 62; ++r) u[r] = U[r * 256 + tid];
.LBB0_170:
	s_or_b64 exec, exec, s[0:1]
	v_lshlrev_b32_sdwa v128, v207, v68 dst_sel:DWORD dst_unused:UNUSED_PAD src0_sel:DWORD src1_sel:BYTE_0
	v_lshl_add_u64 v[0:1], s[6:7], 0, v[128:129]
	v_add_co_u32_e32 v2, vcc, 0x1000, v0
	s_movk_i32 s0, 0x2000
	s_nop 0
	v_addc_co_u32_e32 v3, vcc, 0, v1, vcc
	s_waitcnt lgkmcnt(0)
	s_barrier
	global_load_dword v76, v128, s[6:7]
	global_load_dword v75, v128, s[6:7] offset:1024
	global_load_dword v74, v128, s[6:7] offset:2048
	global_load_dword v73, v128, s[6:7] offset:3072
	global_load_dword v80, v[2:3], off
	global_load_dword v79, v[2:3], off offset:1024
	global_load_dword v78, v[2:3], off offset:2048
	global_load_dword v77, v[2:3], off offset:3072
	v_add_co_u32_e32 v2, vcc, s0, v0
	s_movk_i32 s0, 0x3000
	s_nop 0
	v_addc_co_u32_e32 v3, vcc, 0, v1, vcc
	v_add_co_u32_e32 v4, vcc, s0, v0
	s_movk_i32 s0, 0x4000
	s_nop 0
	v_addc_co_u32_e32 v5, vcc, 0, v1, vcc
	global_load_dword v84, v[4:5], off offset:-4096
	global_load_dword v83, v[2:3], off offset:1024
	global_load_dword v82, v[2:3], off offset:2048
	global_load_dword v81, v[2:3], off offset:3072
	global_load_dword v90, v[4:5], off
	global_load_dword v87, v[4:5], off offset:1024
	global_load_dword v86, v[4:5], off offset:2048
	global_load_dword v85, v[4:5], off offset:3072
	v_add_co_u32_e32 v2, vcc, s0, v0
	s_movk_i32 s0, 0x5000
	s_nop 0
	v_addc_co_u32_e32 v3, vcc, 0, v1, vcc
	v_add_co_u32_e32 v4, vcc, s0, v0
	s_movk_i32 s0, 0x6000
	s_nop 0
	v_addc_co_u32_e32 v5, vcc, 0, v1, vcc
	global_load_dword v105, v[4:5], off offset:-4096
	global_load_dword v103, v[2:3], off offset:1024
	global_load_dword v101, v[2:3], off offset:2048
	global_load_dword v99, v[2:3], off offset:3072
	global_load_dword v97, v[4:5], off
	global_load_dword v95, v[4:5], off offset:1024
	global_load_dword v93, v[4:5], off offset:2048
	global_load_dword v91, v[4:5], off offset:3072
	v_add_co_u32_e32 v2, vcc, s0, v0
	s_movk_i32 s0, 0x7000
	s_nop 0
	v_addc_co_u32_e32 v3, vcc, 0, v1, vcc
	v_add_co_u32_e32 v0, vcc, s0, v0
	v_readlane_b32 s36, v252, 2
	s_nop 0
	v_addc_co_u32_e32 v1, vcc, 0, v1, vcc
	global_load_dword v106, v[0:1], off offset:-4096
	global_load_dword v104, v[2:3], off offset:1024
	global_load_dword v102, v[2:3], off offset:2048
	global_load_dword v100, v[2:3], off offset:3072
	global_load_dword v98, v[0:1], off
	global_load_dword v96, v[0:1], off offset:1024
	global_load_dword v94, v[0:1], off offset:2048
	v_or_b32_sdwa v0, v68, s4 dst_sel:DWORD dst_unused:UNUSED_PAD src0_sel:BYTE_0 src1_sel:DWORD
	v_ashrrev_i32_e32 v1, 31, v0
	v_readlane_b32 s42, v252, 8
	v_readlane_b32 s43, v252, 9
	v_add_u32_e32 v72, s19, v128
	s_lshr_b32 s0, s20, 3
	v_lshl_add_u64 v[0:1], v[0:1], 2, s[42:43]
	global_load_dword v107, v[0:1], off
	ds_read2st64_b32 v[108:109], v72 offset1:4
	ds_read2st64_b32 v[110:111], v72 offset0:8 offset1:12
	ds_read2st64_b32 v[56:57], v72 offset0:16 offset1:20
	ds_read2st64_b32 v[54:55], v72 offset0:24 offset1:28
	ds_read2st64_b32 v[52:53], v72 offset0:32 offset1:36
	ds_read2st64_b32 v[50:51], v72 offset0:40 offset1:44
	ds_read2st64_b32 v[48:49], v72 offset0:48 offset1:52
	ds_read2st64_b32 v[46:47], v72 offset0:56 offset1:60
	ds_read2st64_b32 v[44:45], v72 offset0:64 offset1:68
	ds_read2st64_b32 v[42:43], v72 offset0:72 offset1:76
	ds_read2st64_b32 v[40:41], v72 offset0:80 offset1:84
	ds_read2st64_b32 v[38:39], v72 offset0:88 offset1:92
	ds_read2st64_b32 v[36:37], v72 offset0:96 offset1:100
	ds_read2st64_b32 v[34:35], v72 offset0:104 offset1:108
	ds_read2st64_b32 v[32:33], v72 offset0:112 offset1:116
	ds_read2st64_b32 v[30:31], v72 offset0:120 offset1:124
	ds_read2st64_b32 v[28:29], v72 offset0:128 offset1:132
	ds_read2st64_b32 v[26:27], v72 offset0:136 offset1:140
	ds_read2st64_b32 v[24:25], v72 offset0:144 offset1:148
	ds_read2st64_b32 v[22:23], v72 offset0:152 offset1:156
	ds_read2st64_b32 v[20:21], v72 offset0:160 offset1:164
	ds_read2st64_b32 v[18:19], v72 offset0:168 offset1:172
	ds_read2st64_b32 v[16:17], v72 offset0:176 offset1:180
	ds_read2st64_b32 v[14:15], v72 offset0:184 offset1:188
	ds_read2st64_b32 v[12:13], v72 offset0:192 offset1:196
	ds_read2st64_b32 v[10:11], v72 offset0:200 offset1:204
	ds_read2st64_b32 v[8:9], v72 offset0:208 offset1:212
	ds_read2st64_b32 v[6:7], v72 offset0:216 offset1:220
	ds_read2st64_b32 v[4:5], v72 offset0:224 offset1:228
	ds_read2st64_b32 v[2:3], v72 offset0:232 offset1:236
	ds_read2st64_b32 v[0:1], v72 offset0:240 offset1:244
	s_and_b32 s2, s0, 24
	s_or_b32 s3, s2, 1
	v_cmp_lt_i32_e32 vcc, v204, v200
	s_or_b32 s0, s17, s2
	s_ashr_i32 s1, s0, 31
	s_lshl_b64 s[0:1], s[0:1], 11
	s_mov_b32 s22, 0x3b800000
	v_lshlrev_b32_e32 v92, 3, v67
	v_readlane_b32 s37, v252, 3
	v_readlane_b32 s38, v252, 4
	v_readlane_b32 s39, v252, 5
	v_readlane_b32 s40, v252, 6
	v_readlane_b32 s41, v252, 7
	v_readlane_b32 s44, v252, 10
	v_readlane_b32 s45, v252, 11
	v_readlane_b32 s46, v252, 12
	v_readlane_b32 s47, v252, 13
	v_readlane_b32 s48, v252, 14
	v_readlane_b32 s49, v252, 15
	v_readlane_b32 s50, v252, 16
	v_readlane_b32 s51, v252, 17
	s_waitcnt vmcnt(0) lgkmcnt(14)
; DI void mixer_tile(unsigned char* smem_, const Params& p, int layer, const bf16_t* __restrict__ proj, bf16_t* __restrict__ y, int tile_) {
;     ...
; #pragma unroll
;         for (int t = 0; t < 32; ++t) {
;             float a = bias;
; #pragma unroll
;             for (int k = 0; k < 31; ++k) a += w[k] * u[t + k];
;             U[t * 256 + tid] = a;
;         }
	v_fma_f32 v108, v76, v108, v107
	v_fmac_f32_e32 v108, v75, v109
	v_fma_f32 v109, v76, v109, v107
	v_fmac_f32_e32 v109, v75, v110
	v_fmac_f32_e32 v108, v74, v110
	v_fmac_f32_e32 v109, v74, v111
	v_fmac_f32_e32 v108, v73, v111
	v_fmac_f32_e32 v109, v73, v56
	v_fmac_f32_e32 v108, v80, v56
	v_fmac_f32_e32 v109, v80, v57
	v_fmac_f32_e32 v108, v79, v57
	v_fmac_f32_e32 v109, v79, v54
	v_fmac_f32_e32 v108, v78, v54
	v_fmac_f32_e32 v109, v78, v55
	v_fmac_f32_e32 v108, v77, v55
	v_fmac_f32_e32 v109, v77, v52
	v_fmac_f32_e32 v108, v84, v52
	v_fmac_f32_e32 v109, v84, v53
	v_fmac_f32_e32 v108, v83, v53
	v_fmac_f32_e32 v109, v83, v50
	v_fmac_f32_e32 v108, v82, v50
	v_fmac_f32_e32 v109, v82, v51
	v_fmac_f32_e32 v108, v81, v51
	v_fmac_f32_e32 v109, v81, v48
	v_fmac_f32_e32 v108, v90, v48
	v_fmac_f32_e32 v109, v90, v49
	v_fmac_f32_e32 v108, v87, v49
	v_fmac_f32_e32 v109, v87, v46
	v_fmac_f32_e32 v108, v86, v46
	v_fmac_f32_e32 v109, v86, v47
	v_fmac_f32_e32 v108, v85, v47
	v_fmac_f32_e32 v109, v85, v44
	v_fmac_f32_e32 v108, v105, v44
	v_fmac_f32_e32 v109, v105, v45
	v_fmac_f32_e32 v108, v103, v45
	v_fmac_f32_e32 v109, v103, v42
	v_fmac_f32_e32 v108, v101, v42
	v_fmac_f32_e32 v109, v101, v43
	v_fmac_f32_e32 v108, v99, v43
	v_fmac_f32_e32 v109, v99, v40
	v_fmac_f32_e32 v108, v97, v40
	v_fmac_f32_e32 v109, v97, v41
	v_fmac_f32_e32 v108, v95, v41
	v_fmac_f32_e32 v109, v95, v38
	v_fmac_f32_e32 v108, v93, v38
	v_fmac_f32_e32 v109, v93, v39
	v_fmac_f32_e32 v108, v91, v39
	v_fmac_f32_e32 v109, v91, v36
	v_fmac_f32_e32 v108, v106, v36
	v_fmac_f32_e32 v109, v106, v37
	v_fmac_f32_e32 v108, v104, v37
	v_fmac_f32_e32 v109, v104, v34
	v_fmac_f32_e32 v108, v102, v34
	v_fmac_f32_e32 v109, v102, v35
	v_fmac_f32_e32 v108, v100, v35
	v_fmac_f32_e32 v109, v100, v32
	v_fmac_f32_e32 v108, v98, v32
	v_fmac_f32_e32 v109, v98, v33
	v_fmac_f32_e32 v108, v96, v33
	v_fmac_f32_e32 v109, v96, v30
	v_fmac_f32_e32 v108, v94, v30
	v_fmac_f32_e32 v109, v94, v31
	ds_write2st64_b32 v72, v108, v109 offset1:4
	v_fma_f32 v108, v76, v110, v107
	v_fmac_f32_e32 v108, v75, v111
	v_fma_f32 v109, v76, v111, v107
	v_fmac_f32_e32 v108, v74, v56
	v_fmac_f32_e32 v109, v75, v56
	v_fma_f32 v56, v76, v56, v107
	v_fmac_f32_e32 v108, v73, v57
	v_fmac_f32_e32 v109, v74, v57
	v_fmac_f32_e32 v56, v75, v57
	v_fma_f32 v57, v76, v57, v107
	v_fmac_f32_e32 v108, v80, v54
	v_fmac_f32_e32 v109, v73, v54
	v_fmac_f32_e32 v56, v74, v54
	v_fmac_f32_e32 v57, v75, v54
	v_fma_f32 v54, v76, v54, v107
	v_fmac_f32_e32 v108, v79, v55
	v_fmac_f32_e32 v109, v80, v55
	v_fmac_f32_e32 v56, v73, v55
	v_fmac_f32_e32 v57, v74, v55
	v_fmac_f32_e32 v54, v75, v55
	v_fma_f32 v55, v76, v55, v107
	v_fmac_f32_e32 v108, v78, v52
	v_fmac_f32_e32 v109, v79, v52
	v_fmac_f32_e32 v56, v80, v52
	v_fmac_f32_e32 v57, v73, v52
	v_fmac_f32_e32 v54, v74, v52
	v_fmac_f32_e32 v55, v75, v52
	v_fma_f32 v52, v76, v52, v107
	v_fmac_f32_e32 v108, v77, v53
	v_fmac_f32_e32 v109, v78, v53
	v_fmac_f32_e32 v56, v79, v53
	v_fmac_f32_e32 v57, v80, v53
	v_fmac_f32_e32 v54, v73, v53
	v_fmac_f32_e32 v55, v74, v53
	v_fmac_f32_e32 v52, v75, v53
	v_fma_f32 v53, v76, v53, v107
	v_fmac_f32_e32 v108, v84, v50
	v_fmac_f32_e32 v109, v77, v50
	v_fmac_f32_e32 v56, v78, v50
	v_fmac_f32_e32 v57, v79, v50
	v_fmac_f32_e32 v54, v80, v50
	v_fmac_f32_e32 v55, v73, v50
	v_fmac_f32_e32 v52, v74, v50
	v_fmac_f32_e32 v53, v75, v50
	v_fma_f32 v50, v76, v50, v107
	v_fmac_f32_e32 v108, v83, v51
	v_fmac_f32_e32 v109, v84, v51
	v_fmac_f32_e32 v56, v77, v51
	v_fmac_f32_e32 v57, v78, v51
	v_fmac_f32_e32 v54, v79, v51
	v_fmac_f32_e32 v55, v80, v51
	v_fmac_f32_e32 v52, v73, v51
	v_fmac_f32_e32 v53, v74, v51
	v_fmac_f32_e32 v50, v75, v51
	v_fma_f32 v51, v76, v51, v107
	v_fmac_f32_e32 v108, v82, v48
	v_fmac_f32_e32 v109, v83, v48
	v_fmac_f32_e32 v56, v84, v48
	v_fmac_f32_e32 v57, v77, v48
	v_fmac_f32_e32 v54, v78, v48
	v_fmac_f32_e32 v55, v79, v48
	v_fmac_f32_e32 v52, v80, v48
	v_fmac_f32_e32 v53, v73, v48
	v_fmac_f32_e32 v50, v74, v48
	v_fmac_f32_e32 v51, v75, v48
	v_fma_f32 v48, v76, v48, v107
	v_fmac_f32_e32 v108, v81, v49
	v_fmac_f32_e32 v109, v82, v49
	v_fmac_f32_e32 v56, v83, v49
	v_fmac_f32_e32 v57, v84, v49
	v_fmac_f32_e32 v54, v77, v49
	v_fmac_f32_e32 v55, v78, v49
	v_fmac_f32_e32 v52, v79, v49
	v_fmac_f32_e32 v53, v80, v49
	v_fmac_f32_e32 v50, v73, v49
	v_fmac_f32_e32 v51, v74, v49
	v_fmac_f32_e32 v48, v75, v49
	v_fma_f32 v49, v76, v49, v107
	v_fmac_f32_e32 v108, v90, v46
	v_fmac_f32_e32 v109, v81, v46
	v_fmac_f32_e32 v56, v82, v46
	v_fmac_f32_e32 v57, v83, v46
	v_fmac_f32_e32 v54, v84, v46
	v_fmac_f32_e32 v55, v77, v46
	v_fmac_f32_e32 v52, v78, v46
	v_fmac_f32_e32 v53, v79, v46
	v_fmac_f32_e32 v50, v80, v46
	v_fmac_f32_e32 v51, v73, v46
	v_fmac_f32_e32 v48, v74, v46
	v_fmac_f32_e32 v49, v75, v46
	v_fma_f32 v46, v76, v46, v107
	v_fmac_f32_e32 v108, v87, v47
	v_fmac_f32_e32 v109, v90, v47
	v_fmac_f32_e32 v56, v81, v47
	v_fmac_f32_e32 v57, v82, v47
	v_fmac_f32_e32 v54, v83, v47
	v_fmac_f32_e32 v55, v84, v47
	v_fmac_f32_e32 v52, v77, v47
	v_fmac_f32_e32 v53, v78, v47
	v_fmac_f32_e32 v50, v79, v47
	v_fmac_f32_e32 v51, v80, v47
	v_fmac_f32_e32 v48, v73, v47
	v_fmac_f32_e32 v49, v74, v47
	v_fmac_f32_e32 v46, v75, v47
	v_fma_f32 v47, v76, v47, v107
	v_fmac_f32_e32 v108, v86, v44
	v_fmac_f32_e32 v109, v87, v44
	v_fmac_f32_e32 v56, v90, v44
	v_fmac_f32_e32 v57, v81, v44
	v_fmac_f32_e32 v54, v82, v44
	v_fmac_f32_e32 v55, v83, v44
	v_fmac_f32_e32 v52, v84, v44
	v_fmac_f32_e32 v53, v77, v44
	v_fmac_f32_e32 v50, v78, v44
	v_fmac_f32_e32 v51, v79, v44
	v_fmac_f32_e32 v48, v80, v44
	v_fmac_f32_e32 v49, v73, v44
	v_fmac_f32_e32 v46, v74, v44
	v_fmac_f32_e32 v47, v75, v44
	v_fma_f32 v44, v76, v44, v107
; DI void mixer_tile(unsigned char* smem_, const Params& p, int layer, const bf16_t* __restrict__ proj, bf16_t* __restrict__ y, int tile_) {
;     ...
; #pragma unroll
;         for (int t = 0; t < 32; ++t) {
;             float a = bias;
; #pragma unroll
;             for (int k = 0; k < 31; ++k) a += w[k] * u[t + k];
;             U[t * 256 + tid] = a;
;         }
	v_fmac_f32_e32 v108, v85, v45
	v_fmac_f32_e32 v109, v86, v45
	v_fmac_f32_e32 v56, v87, v45
	v_fmac_f32_e32 v57, v90, v45
	v_fmac_f32_e32 v54, v81, v45
	v_fmac_f32_e32 v55, v82, v45
	v_fmac_f32_e32 v52, v83, v45
	v_fmac_f32_e32 v53, v84, v45
	v_fmac_f32_e32 v50, v77, v45
	v_fmac_f32_e32 v51, v78, v45
	v_fmac_f32_e32 v48, v79, v45
	v_fmac_f32_e32 v49, v80, v45
	v_fmac_f32_e32 v46, v73, v45
	v_fmac_f32_e32 v47, v74, v45
	v_fmac_f32_e32 v44, v75, v45
	v_fma_f32 v45, v76, v45, v107
	v_fmac_f32_e32 v108, v105, v42
	v_fmac_f32_e32 v109, v85, v42
	v_fmac_f32_e32 v56, v86, v42
	v_fmac_f32_e32 v57, v87, v42
	v_fmac_f32_e32 v54, v90, v42
	v_fmac_f32_e32 v55, v81, v42
	v_fmac_f32_e32 v52, v82, v42
	v_fmac_f32_e32 v53, v83, v42
	v_fmac_f32_e32 v50, v84, v42
	v_fmac_f32_e32 v51, v77, v42
	v_fmac_f32_e32 v48, v78, v42
	v_fmac_f32_e32 v49, v79, v42
	v_fmac_f32_e32 v46, v80, v42
	v_fmac_f32_e32 v47, v73, v42
	v_fmac_f32_e32 v44, v74, v42
	v_fmac_f32_e32 v45, v75, v42
	v_fma_f32 v42, v76, v42, v107
	v_fmac_f32_e32 v108, v103, v43
	v_fmac_f32_e32 v109, v105, v43
	v_fmac_f32_e32 v56, v85, v43
	v_fmac_f32_e32 v57, v86, v43
	v_fmac_f32_e32 v54, v87, v43
	v_fmac_f32_e32 v55, v90, v43
	v_fmac_f32_e32 v52, v81, v43
	v_fmac_f32_e32 v53, v82, v43
	v_fmac_f32_e32 v50, v83, v43
	v_fmac_f32_e32 v51, v84, v43
	v_fmac_f32_e32 v48, v77, v43
	v_fmac_f32_e32 v49, v78, v43
	v_fmac_f32_e32 v46, v79, v43
	v_fmac_f32_e32 v47, v80, v43
	v_fmac_f32_e32 v44, v73, v43
	v_fmac_f32_e32 v45, v74, v43
	v_fmac_f32_e32 v42, v75, v43
	v_fma_f32 v43, v76, v43, v107
	v_fmac_f32_e32 v108, v101, v40
	v_fmac_f32_e32 v109, v103, v40
	v_fmac_f32_e32 v56, v105, v40
	v_fmac_f32_e32 v57, v85, v40
	v_fmac_f32_e32 v54, v86, v40
	v_fmac_f32_e32 v55, v87, v40
	v_fmac_f32_e32 v52, v90, v40
	v_fmac_f32_e32 v53, v81, v40
	v_fmac_f32_e32 v50, v82, v40
	v_fmac_f32_e32 v51, v83, v40
	v_fmac_f32_e32 v48, v84, v40
	v_fmac_f32_e32 v49, v77, v40
	v_fmac_f32_e32 v46, v78, v40
	v_fmac_f32_e32 v47, v79, v40
	v_fmac_f32_e32 v44, v80, v40
	v_fmac_f32_e32 v45, v73, v40
	v_fmac_f32_e32 v42, v74, v40
	v_fmac_f32_e32 v43, v75, v40
	v_fma_f32 v40, v76, v40, v107
	v_fmac_f32_e32 v108, v99, v41
	v_fmac_f32_e32 v109, v101, v41
	v_fmac_f32_e32 v56, v103, v41
	v_fmac_f32_e32 v57, v105, v41
	v_fmac_f32_e32 v54, v85, v41
	v_fmac_f32_e32 v55, v86, v41
	v_fmac_f32_e32 v52, v87, v41
	v_fmac_f32_e32 v53, v90, v41
	v_fmac_f32_e32 v50, v81, v41
	v_fmac_f32_e32 v51, v82, v41
	v_fmac_f32_e32 v48, v83, v41
	v_fmac_f32_e32 v49, v84, v41
	v_fmac_f32_e32 v46, v77, v41
	v_fmac_f32_e32 v47, v78, v41
	v_fmac_f32_e32 v44, v79, v41
	v_fmac_f32_e32 v45, v80, v41
	v_fmac_f32_e32 v42, v73, v41
	v_fmac_f32_e32 v43, v74, v41
	v_fmac_f32_e32 v40, v75, v41
	v_fma_f32 v41, v76, v41, v107
	v_fmac_f32_e32 v108, v97, v38
	v_fmac_f32_e32 v109, v99, v38
	v_fmac_f32_e32 v56, v101, v38
	v_fmac_f32_e32 v57, v103, v38
	v_fmac_f32_e32 v54, v105, v38
	v_fmac_f32_e32 v55, v85, v38
	v_fmac_f32_e32 v52, v86, v38
	v_fmac_f32_e32 v53, v87, v38
	v_fmac_f32_e32 v50, v90, v38
	v_fmac_f32_e32 v51, v81, v38
	v_fmac_f32_e32 v48, v82, v38
	v_fmac_f32_e32 v49, v83, v38
	v_fmac_f32_e32 v46, v84, v38
	v_fmac_f32_e32 v47, v77, v38
	v_fmac_f32_e32 v44, v78, v38
	v_fmac_f32_e32 v45, v79, v38
	v_fmac_f32_e32 v42, v80, v38
	v_fmac_f32_e32 v43, v73, v38
	v_fmac_f32_e32 v40, v74, v38
	v_fmac_f32_e32 v41, v75, v38
	v_fma_f32 v38, v76, v38, v107
	v_fmac_f32_e32 v108, v95, v39
	v_fmac_f32_e32 v109, v97, v39
	v_fmac_f32_e32 v56, v99, v39
	v_fmac_f32_e32 v57, v101, v39
	v_fmac_f32_e32 v54, v103, v39
	v_fmac_f32_e32 v55, v105, v39
	v_fmac_f32_e32 v52, v85, v39
	v_fmac_f32_e32 v53, v86, v39
	v_fmac_f32_e32 v50, v87, v39
	v_fmac_f32_e32 v51, v90, v39
	v_fmac_f32_e32 v48, v81, v39
	v_fmac_f32_e32 v49, v82, v39
	v_fmac_f32_e32 v46, v83, v39
	v_fmac_f32_e32 v47, v84, v39
	v_fmac_f32_e32 v44, v77, v39
	v_fmac_f32_e32 v45, v78, v39
	v_fmac_f32_e32 v42, v79, v39
	v_fmac_f32_e32 v43, v80, v39
	v_fmac_f32_e32 v40, v73, v39
	v_fmac_f32_e32 v41, v74, v39
	v_fmac_f32_e32 v38, v75, v39
	v_fma_f32 v39, v76, v39, v107
	v_fmac_f32_e32 v108, v93, v36
	v_fmac_f32_e32 v109, v95, v36
	v_fmac_f32_e32 v56, v97, v36
	v_fmac_f32_e32 v57, v99, v36
	v_fmac_f32_e32 v54, v101, v36
	v_fmac_f32_e32 v55, v103, v36
	v_fmac_f32_e32 v52, v105, v36
	v_fmac_f32_e32 v53, v85, v36
	v_fmac_f32_e32 v50, v86, v36
	v_fmac_f32_e32 v51, v87, v36
	v_fmac_f32_e32 v48, v90, v36
	v_fmac_f32_e32 v49, v81, v36
	v_fmac_f32_e32 v46, v82, v36
	v_fmac_f32_e32 v47, v83, v36
	v_fmac_f32_e32 v44, v84, v36
	v_fmac_f32_e32 v45, v77, v36
	v_fmac_f32_e32 v42, v78, v36
	v_fmac_f32_e32 v43, v79, v36
	v_fmac_f32_e32 v40, v80, v36
	v_fmac_f32_e32 v41, v73, v36
	v_fmac_f32_e32 v38, v74, v36
	v_fmac_f32_e32 v39, v75, v36
	v_fma_f32 v36, v76, v36, v107
	v_fmac_f32_e32 v108, v91, v37
	v_fmac_f32_e32 v109, v93, v37
	v_fmac_f32_e32 v56, v95, v37
	v_fmac_f32_e32 v57, v97, v37
	v_fmac_f32_e32 v54, v99, v37
	v_fmac_f32_e32 v55, v101, v37
	v_fmac_f32_e32 v52, v103, v37
	v_fmac_f32_e32 v53, v105, v37
	v_fmac_f32_e32 v50, v85, v37
	v_fmac_f32_e32 v51, v86, v37
	v_fmac_f32_e32 v48, v87, v37
	v_fmac_f32_e32 v49, v90, v37
	v_fmac_f32_e32 v46, v81, v37
	v_fmac_f32_e32 v47, v82, v37
	v_fmac_f32_e32 v44, v83, v37
	v_fmac_f32_e32 v45, v84, v37
	v_fmac_f32_e32 v42, v77, v37
	v_fmac_f32_e32 v43, v78, v37
	v_fmac_f32_e32 v40, v79, v37
	v_fmac_f32_e32 v41, v80, v37
	v_fmac_f32_e32 v38, v73, v37
	v_fmac_f32_e32 v39, v74, v37
	v_fmac_f32_e32 v36, v75, v37
	v_fma_f32 v37, v76, v37, v107
	v_fmac_f32_e32 v108, v106, v34
	v_fmac_f32_e32 v109, v91, v34
	v_fmac_f32_e32 v56, v93, v34
	v_fmac_f32_e32 v57, v95, v34
	v_fmac_f32_e32 v54, v97, v34
	v_fmac_f32_e32 v55, v99, v34
; DI void mixer_tile(unsigned char* smem_, const Params& p, int layer, const bf16_t* __restrict__ proj, bf16_t* __restrict__ y, int tile_) {
;     ...
; #pragma unroll
;         for (int t = 0; t < 32; ++t) {
;             float a = bias;
; #pragma unroll
;             for (int k = 0; k < 31; ++k) a += w[k] * u[t + k];
;             U[t * 256 + tid] = a;
;         }
	v_fmac_f32_e32 v52, v101, v34
	v_fmac_f32_e32 v53, v103, v34
	v_fmac_f32_e32 v50, v105, v34
	v_fmac_f32_e32 v51, v85, v34
	v_fmac_f32_e32 v48, v86, v34
	v_fmac_f32_e32 v49, v87, v34
	v_fmac_f32_e32 v46, v90, v34
	v_fmac_f32_e32 v47, v81, v34
	v_fmac_f32_e32 v44, v82, v34
	v_fmac_f32_e32 v45, v83, v34
	v_fmac_f32_e32 v42, v84, v34
	v_fmac_f32_e32 v43, v77, v34
	v_fmac_f32_e32 v40, v78, v34
	v_fmac_f32_e32 v41, v79, v34
	v_fmac_f32_e32 v38, v80, v34
	v_fmac_f32_e32 v39, v73, v34
	v_fmac_f32_e32 v36, v74, v34
	v_fmac_f32_e32 v37, v75, v34
	v_fma_f32 v34, v76, v34, v107
	v_fmac_f32_e32 v108, v104, v35
	v_fmac_f32_e32 v109, v106, v35
	v_fmac_f32_e32 v56, v91, v35
	v_fmac_f32_e32 v57, v93, v35
	v_fmac_f32_e32 v54, v95, v35
	v_fmac_f32_e32 v55, v97, v35
	v_fmac_f32_e32 v52, v99, v35
	v_fmac_f32_e32 v53, v101, v35
	v_fmac_f32_e32 v50, v103, v35
	v_fmac_f32_e32 v51, v105, v35
	v_fmac_f32_e32 v48, v85, v35
	v_fmac_f32_e32 v49, v86, v35
	v_fmac_f32_e32 v46, v87, v35
	v_fmac_f32_e32 v47, v90, v35
	v_fmac_f32_e32 v44, v81, v35
	v_fmac_f32_e32 v45, v82, v35
	v_fmac_f32_e32 v42, v83, v35
	v_fmac_f32_e32 v43, v84, v35
	v_fmac_f32_e32 v40, v77, v35
	v_fmac_f32_e32 v41, v78, v35
	v_fmac_f32_e32 v38, v79, v35
	v_fmac_f32_e32 v39, v80, v35
	v_fmac_f32_e32 v36, v73, v35
	v_fmac_f32_e32 v37, v74, v35
	v_fmac_f32_e32 v34, v75, v35
	v_fma_f32 v35, v76, v35, v107
	v_fmac_f32_e32 v108, v102, v32
	v_fmac_f32_e32 v109, v104, v32
	v_fmac_f32_e32 v56, v106, v32
	v_fmac_f32_e32 v57, v91, v32
	v_fmac_f32_e32 v54, v93, v32
	v_fmac_f32_e32 v55, v95, v32
	v_fmac_f32_e32 v52, v97, v32
	v_fmac_f32_e32 v53, v99, v32
	v_fmac_f32_e32 v50, v101, v32
	v_fmac_f32_e32 v51, v103, v32
	v_fmac_f32_e32 v48, v105, v32
	v_fmac_f32_e32 v49, v85, v32
	v_fmac_f32_e32 v46, v86, v32
	v_fmac_f32_e32 v47, v87, v32
	v_fmac_f32_e32 v44, v90, v32
	v_fmac_f32_e32 v45, v81, v32
	v_fmac_f32_e32 v42, v82, v32
	v_fmac_f32_e32 v43, v83, v32
	v_fmac_f32_e32 v40, v84, v32
	v_fmac_f32_e32 v41, v77, v32
	v_fmac_f32_e32 v38, v78, v32
	v_fmac_f32_e32 v39, v79, v32
	v_fmac_f32_e32 v36, v80, v32
	v_fmac_f32_e32 v37, v73, v32
	v_fmac_f32_e32 v34, v74, v32
	v_fmac_f32_e32 v35, v75, v32
	v_fma_f32 v32, v76, v32, v107
	v_fmac_f32_e32 v108, v100, v33
	v_fmac_f32_e32 v109, v102, v33
	v_fmac_f32_e32 v56, v104, v33
	v_fmac_f32_e32 v57, v106, v33
	v_fmac_f32_e32 v54, v91, v33
	v_fmac_f32_e32 v55, v93, v33
	v_fmac_f32_e32 v52, v95, v33
	v_fmac_f32_e32 v53, v97, v33
	v_fmac_f32_e32 v50, v99, v33
	v_fmac_f32_e32 v51, v101, v33
	v_fmac_f32_e32 v48, v103, v33
	v_fmac_f32_e32 v49, v105, v33
	v_fmac_f32_e32 v46, v85, v33
	v_fmac_f32_e32 v47, v86, v33
	v_fmac_f32_e32 v44, v87, v33
	v_fmac_f32_e32 v45, v90, v33
	v_fmac_f32_e32 v42, v81, v33
	v_fmac_f32_e32 v43, v82, v33
	v_fmac_f32_e32 v40, v83, v33
	v_fmac_f32_e32 v41, v84, v33
	v_fmac_f32_e32 v38, v77, v33
	v_fmac_f32_e32 v39, v78, v33
	v_fmac_f32_e32 v36, v79, v33
	v_fmac_f32_e32 v37, v80, v33
	v_fmac_f32_e32 v34, v73, v33
	v_fmac_f32_e32 v35, v74, v33
	v_fmac_f32_e32 v32, v75, v33
	v_fma_f32 v33, v76, v33, v107
	v_fmac_f32_e32 v108, v98, v30
	v_fmac_f32_e32 v109, v100, v30
	v_fmac_f32_e32 v56, v102, v30
	v_fmac_f32_e32 v57, v104, v30
	v_fmac_f32_e32 v54, v106, v30
	v_fmac_f32_e32 v55, v91, v30
	v_fmac_f32_e32 v52, v93, v30
	v_fmac_f32_e32 v53, v95, v30
	v_fmac_f32_e32 v50, v97, v30
	v_fmac_f32_e32 v51, v99, v30
	v_fmac_f32_e32 v48, v101, v30
	v_fmac_f32_e32 v49, v103, v30
	v_fmac_f32_e32 v46, v105, v30
	v_fmac_f32_e32 v47, v85, v30
	v_fmac_f32_e32 v44, v86, v30
	v_fmac_f32_e32 v45, v87, v30
	v_fmac_f32_e32 v42, v90, v30
	v_fmac_f32_e32 v43, v81, v30
	v_fmac_f32_e32 v40, v82, v30
	v_fmac_f32_e32 v41, v83, v30
	v_fmac_f32_e32 v38, v84, v30
	v_fmac_f32_e32 v39, v77, v30
	v_fmac_f32_e32 v36, v78, v30
	v_fmac_f32_e32 v37, v79, v30
	v_fmac_f32_e32 v34, v80, v30
	v_fmac_f32_e32 v35, v73, v30
	v_fmac_f32_e32 v32, v74, v30
	v_fmac_f32_e32 v33, v75, v30
	v_fma_f32 v30, v76, v30, v107
	v_fmac_f32_e32 v30, v75, v31
	v_fmac_f32_e32 v107, v76, v31
	v_fmac_f32_e32 v33, v74, v31
	v_fmac_f32_e32 v30, v74, v28
	v_fmac_f32_e32 v107, v75, v28
	v_fmac_f32_e32 v32, v73, v31
	v_fmac_f32_e32 v33, v73, v28
	v_fmac_f32_e32 v30, v73, v29
	v_fmac_f32_e32 v107, v74, v29
	v_fmac_f32_e32 v32, v80, v28
	v_fmac_f32_e32 v33, v80, v29
	s_waitcnt lgkmcnt(14)
	v_fmac_f32_e32 v30, v80, v26
	v_fmac_f32_e32 v107, v73, v26
	v_fmac_f32_e32 v32, v79, v29
	v_fmac_f32_e32 v33, v79, v26
	v_fmac_f32_e32 v30, v79, v27
	v_fmac_f32_e32 v107, v80, v27
	v_fmac_f32_e32 v35, v80, v31
	v_fmac_f32_e32 v32, v78, v26
	v_fmac_f32_e32 v33, v78, v27
	s_waitcnt lgkmcnt(13)
	v_fmac_f32_e32 v30, v78, v24
	v_fmac_f32_e32 v107, v79, v24
	v_fmac_f32_e32 v34, v79, v31
	v_fmac_f32_e32 v35, v79, v28
	v_fmac_f32_e32 v32, v77, v27
	v_fmac_f32_e32 v33, v77, v24
	v_fmac_f32_e32 v30, v77, v25
	v_fmac_f32_e32 v107, v78, v25
	v_fmac_f32_e32 v37, v78, v31
	v_fmac_f32_e32 v34, v78, v28
	v_fmac_f32_e32 v35, v78, v29
	v_fmac_f32_e32 v32, v84, v24
	v_fmac_f32_e32 v33, v84, v25
	s_waitcnt lgkmcnt(12)
	v_fmac_f32_e32 v30, v84, v22
	v_fmac_f32_e32 v107, v77, v22
	v_fmac_f32_e32 v36, v77, v31
	v_fmac_f32_e32 v37, v77, v28
	v_fmac_f32_e32 v34, v77, v29
	v_fmac_f32_e32 v35, v77, v26
	v_fmac_f32_e32 v32, v83, v25
	v_fmac_f32_e32 v33, v83, v22
	v_fmac_f32_e32 v30, v83, v23
	v_fmac_f32_e32 v107, v84, v23
	v_fmac_f32_e32 v39, v84, v31
	v_fmac_f32_e32 v36, v84, v28
	v_fmac_f32_e32 v37, v84, v29
	v_fmac_f32_e32 v34, v84, v26
	v_fmac_f32_e32 v35, v84, v27
	v_fmac_f32_e32 v32, v82, v22
	v_fmac_f32_e32 v33, v82, v23
	s_waitcnt lgkmcnt(11)
; DI void mixer_tile(unsigned char* smem_, const Params& p, int layer, const bf16_t* __restrict__ proj, bf16_t* __restrict__ y, int tile_) {
;     ...
; #pragma unroll
;         for (int t = 0; t < 32; ++t) {
;             float a = bias;
; #pragma unroll
;             for (int k = 0; k < 31; ++k) a += w[k] * u[t + k];
;             U[t * 256 + tid] = a;
;         }
	v_fmac_f32_e32 v30, v82, v20
	v_fmac_f32_e32 v107, v83, v20
	v_fmac_f32_e32 v38, v83, v31
	v_fmac_f32_e32 v39, v83, v28
	v_fmac_f32_e32 v36, v83, v29
	v_fmac_f32_e32 v37, v83, v26
	v_fmac_f32_e32 v34, v83, v27
	v_fmac_f32_e32 v35, v83, v24
	v_fmac_f32_e32 v32, v81, v23
	v_fmac_f32_e32 v33, v81, v20
	v_fmac_f32_e32 v30, v81, v21
	v_fmac_f32_e32 v107, v82, v21
	v_fmac_f32_e32 v41, v82, v31
	v_fmac_f32_e32 v38, v82, v28
	v_fmac_f32_e32 v39, v82, v29
	v_fmac_f32_e32 v36, v82, v26
	v_fmac_f32_e32 v37, v82, v27
	v_fmac_f32_e32 v34, v82, v24
	v_fmac_f32_e32 v35, v82, v25
	v_fmac_f32_e32 v32, v90, v20
	v_fmac_f32_e32 v33, v90, v21
	s_waitcnt lgkmcnt(10)
	v_fmac_f32_e32 v30, v90, v18
	v_fmac_f32_e32 v107, v81, v18
	v_fmac_f32_e32 v40, v81, v31
	v_fmac_f32_e32 v41, v81, v28
	v_fmac_f32_e32 v38, v81, v29
	v_fmac_f32_e32 v39, v81, v26
	v_fmac_f32_e32 v36, v81, v27
	v_fmac_f32_e32 v37, v81, v24
	v_fmac_f32_e32 v34, v81, v25
	v_fmac_f32_e32 v35, v81, v22
	v_fmac_f32_e32 v32, v87, v21
	v_fmac_f32_e32 v33, v87, v18
	v_fmac_f32_e32 v30, v87, v19
	v_fmac_f32_e32 v107, v90, v19
	v_fmac_f32_e32 v43, v90, v31
	v_fmac_f32_e32 v40, v90, v28
	v_fmac_f32_e32 v41, v90, v29
	v_fmac_f32_e32 v38, v90, v26
	v_fmac_f32_e32 v39, v90, v27
	v_fmac_f32_e32 v36, v90, v24
	v_fmac_f32_e32 v37, v90, v25
	v_fmac_f32_e32 v34, v90, v22
	v_fmac_f32_e32 v35, v90, v23
	v_fmac_f32_e32 v32, v86, v18
	v_fmac_f32_e32 v33, v86, v19
	s_waitcnt lgkmcnt(9)
	v_fmac_f32_e32 v30, v86, v16
	v_fmac_f32_e32 v107, v87, v16
	v_fmac_f32_e32 v42, v87, v31
	v_fmac_f32_e32 v43, v87, v28
	v_fmac_f32_e32 v40, v87, v29
	v_fmac_f32_e32 v41, v87, v26
	v_fmac_f32_e32 v38, v87, v27
	v_fmac_f32_e32 v39, v87, v24
	v_fmac_f32_e32 v36, v87, v25
	v_fmac_f32_e32 v37, v87, v22
	v_fmac_f32_e32 v34, v87, v23
	v_fmac_f32_e32 v35, v87, v20
	v_fmac_f32_e32 v32, v85, v19
	v_fmac_f32_e32 v33, v85, v16
	v_fmac_f32_e32 v30, v85, v17
	v_fmac_f32_e32 v107, v86, v17
	v_fmac_f32_e32 v45, v86, v31
	v_fmac_f32_e32 v42, v86, v28
	v_fmac_f32_e32 v43, v86, v29
	v_fmac_f32_e32 v40, v86, v26
	v_fmac_f32_e32 v41, v86, v27
	v_fmac_f32_e32 v38, v86, v24
	v_fmac_f32_e32 v39, v86, v25
	v_fmac_f32_e32 v36, v86, v22
	v_fmac_f32_e32 v37, v86, v23
	v_fmac_f32_e32 v34, v86, v20
	v_fmac_f32_e32 v35, v86, v21
	v_fmac_f32_e32 v32, v105, v16
	v_fmac_f32_e32 v33, v105, v17
	s_waitcnt lgkmcnt(8)
	v_fmac_f32_e32 v30, v105, v14
	v_fmac_f32_e32 v107, v85, v14
	v_fmac_f32_e32 v44, v85, v31
	v_fmac_f32_e32 v45, v85, v28
	v_fmac_f32_e32 v42, v85, v29
	v_fmac_f32_e32 v43, v85, v26
	v_fmac_f32_e32 v40, v85, v27
	v_fmac_f32_e32 v41, v85, v24
	v_fmac_f32_e32 v38, v85, v25
	v_fmac_f32_e32 v39, v85, v22
	v_fmac_f32_e32 v36, v85, v23
	v_fmac_f32_e32 v37, v85, v20
	v_fmac_f32_e32 v34, v85, v21
	v_fmac_f32_e32 v35, v85, v18
	v_fmac_f32_e32 v32, v103, v17
	v_fmac_f32_e32 v33, v103, v14
	v_fmac_f32_e32 v30, v103, v15
	v_fmac_f32_e32 v107, v105, v15
	v_fmac_f32_e32 v47, v105, v31
	v_fmac_f32_e32 v44, v105, v28
	v_fmac_f32_e32 v45, v105, v29
	v_fmac_f32_e32 v42, v105, v26
	v_fmac_f32_e32 v43, v105, v27
	v_fmac_f32_e32 v40, v105, v24
	v_fmac_f32_e32 v41, v105, v25
	v_fmac_f32_e32 v38, v105, v22
	v_fmac_f32_e32 v39, v105, v23
	v_fmac_f32_e32 v36, v105, v20
	v_fmac_f32_e32 v37, v105, v21
	v_fmac_f32_e32 v34, v105, v18
	v_fmac_f32_e32 v35, v105, v19
	v_fmac_f32_e32 v32, v101, v14
	v_fmac_f32_e32 v33, v101, v15
	s_waitcnt lgkmcnt(7)
	v_fmac_f32_e32 v30, v101, v12
	v_fmac_f32_e32 v107, v103, v12
	v_fmac_f32_e32 v46, v103, v31
	v_fmac_f32_e32 v47, v103, v28
	v_fmac_f32_e32 v44, v103, v29
	v_fmac_f32_e32 v45, v103, v26
	v_fmac_f32_e32 v42, v103, v27
	v_fmac_f32_e32 v43, v103, v24
	v_fmac_f32_e32 v40, v103, v25
	v_fmac_f32_e32 v41, v103, v22
	v_fmac_f32_e32 v38, v103, v23
	v_fmac_f32_e32 v39, v103, v20
	v_fmac_f32_e32 v36, v103, v21
	v_fmac_f32_e32 v37, v103, v18
	v_fmac_f32_e32 v34, v103, v19
	v_fmac_f32_e32 v35, v103, v16
	v_fmac_f32_e32 v32, v99, v15
	v_fmac_f32_e32 v33, v99, v12
	v_fmac_f32_e32 v30, v99, v13
	v_fmac_f32_e32 v107, v101, v13
	v_fmac_f32_e32 v49, v101, v31
	v_fmac_f32_e32 v46, v101, v28
	v_fmac_f32_e32 v47, v101, v29
	v_fmac_f32_e32 v44, v101, v26
	v_fmac_f32_e32 v45, v101, v27
	v_fmac_f32_e32 v42, v101, v24
	v_fmac_f32_e32 v43, v101, v25
	v_fmac_f32_e32 v40, v101, v22
	v_fmac_f32_e32 v41, v101, v23
	v_fmac_f32_e32 v38, v101, v20
	v_fmac_f32_e32 v39, v101, v21
	v_fmac_f32_e32 v36, v101, v18
	v_fmac_f32_e32 v37, v101, v19
	v_fmac_f32_e32 v34, v101, v16
	v_fmac_f32_e32 v35, v101, v17
	v_fmac_f32_e32 v32, v97, v12
	v_fmac_f32_e32 v33, v97, v13
	s_waitcnt lgkmcnt(6)
	v_fmac_f32_e32 v30, v97, v10
	v_fmac_f32_e32 v107, v99, v10
	v_fmac_f32_e32 v48, v99, v31
	v_fmac_f32_e32 v49, v99, v28
	v_fmac_f32_e32 v46, v99, v29
	v_fmac_f32_e32 v47, v99, v26
	v_fmac_f32_e32 v44, v99, v27
	v_fmac_f32_e32 v45, v99, v24
	v_fmac_f32_e32 v42, v99, v25
	v_fmac_f32_e32 v43, v99, v22
	v_fmac_f32_e32 v40, v99, v23
	v_fmac_f32_e32 v41, v99, v20
	v_fmac_f32_e32 v38, v99, v21
	v_fmac_f32_e32 v39, v99, v18
	v_fmac_f32_e32 v36, v99, v19
	v_fmac_f32_e32 v37, v99, v16
	v_fmac_f32_e32 v34, v99, v17
	v_fmac_f32_e32 v35, v99, v14
	v_fmac_f32_e32 v32, v95, v13
	v_fmac_f32_e32 v33, v95, v10
	v_fmac_f32_e32 v30, v95, v11
	v_fmac_f32_e32 v107, v97, v11
	v_fmac_f32_e32 v51, v97, v31
	v_fmac_f32_e32 v48, v97, v28
	v_fmac_f32_e32 v49, v97, v29
	v_fmac_f32_e32 v46, v97, v26
	v_fmac_f32_e32 v47, v97, v27
	v_fmac_f32_e32 v44, v97, v24
	v_fmac_f32_e32 v45, v97, v25
	v_fmac_f32_e32 v42, v97, v22
	v_fmac_f32_e32 v43, v97, v23
	v_fmac_f32_e32 v40, v97, v20
	v_fmac_f32_e32 v41, v97, v21
	v_fmac_f32_e32 v38, v97, v18
	v_fmac_f32_e32 v39, v97, v19
	v_fmac_f32_e32 v36, v97, v16
	v_fmac_f32_e32 v37, v97, v17
	v_fmac_f32_e32 v34, v97, v14
	v_fmac_f32_e32 v35, v97, v15
	v_fmac_f32_e32 v32, v93, v10
	v_fmac_f32_e32 v33, v93, v11
	s_waitcnt lgkmcnt(5)
; DI void mixer_tile(unsigned char* smem_, const Params& p, int layer, const bf16_t* __restrict__ proj, bf16_t* __restrict__ y, int tile_) {
;     ...
; #pragma unroll
;         for (int t = 0; t < 32; ++t) {
;             float a = bias;
; #pragma unroll
;             for (int k = 0; k < 31; ++k) a += w[k] * u[t + k];
;             U[t * 256 + tid] = a;
;         }
	v_fmac_f32_e32 v30, v93, v8
	v_fmac_f32_e32 v107, v95, v8
	v_fmac_f32_e32 v50, v95, v31
	v_fmac_f32_e32 v51, v95, v28
	v_fmac_f32_e32 v48, v95, v29
	v_fmac_f32_e32 v49, v95, v26
	v_fmac_f32_e32 v46, v95, v27
	v_fmac_f32_e32 v47, v95, v24
	v_fmac_f32_e32 v44, v95, v25
	v_fmac_f32_e32 v45, v95, v22
	v_fmac_f32_e32 v42, v95, v23
	v_fmac_f32_e32 v43, v95, v20
	v_fmac_f32_e32 v40, v95, v21
	v_fmac_f32_e32 v41, v95, v18
	v_fmac_f32_e32 v38, v95, v19
	v_fmac_f32_e32 v39, v95, v16
	v_fmac_f32_e32 v36, v95, v17
	v_fmac_f32_e32 v37, v95, v14
	v_fmac_f32_e32 v34, v95, v15
	v_fmac_f32_e32 v35, v95, v12
	v_fmac_f32_e32 v32, v91, v11
	v_fmac_f32_e32 v33, v91, v8
	v_fmac_f32_e32 v30, v91, v9
	v_fmac_f32_e32 v107, v93, v9
	v_fmac_f32_e32 v53, v93, v31
	v_fmac_f32_e32 v50, v93, v28
	v_fmac_f32_e32 v51, v93, v29
	v_fmac_f32_e32 v48, v93, v26
	v_fmac_f32_e32 v49, v93, v27
	v_fmac_f32_e32 v46, v93, v24
	v_fmac_f32_e32 v47, v93, v25
	v_fmac_f32_e32 v44, v93, v22
	v_fmac_f32_e32 v45, v93, v23
	v_fmac_f32_e32 v42, v93, v20
	v_fmac_f32_e32 v43, v93, v21
	v_fmac_f32_e32 v40, v93, v18
	v_fmac_f32_e32 v41, v93, v19
	v_fmac_f32_e32 v38, v93, v16
	v_fmac_f32_e32 v39, v93, v17
	v_fmac_f32_e32 v36, v93, v14
	v_fmac_f32_e32 v37, v93, v15
	v_fmac_f32_e32 v34, v93, v12
	v_fmac_f32_e32 v35, v93, v13
	v_fmac_f32_e32 v32, v106, v8
	v_fmac_f32_e32 v33, v106, v9
	s_waitcnt lgkmcnt(4)
	v_fmac_f32_e32 v30, v106, v6
	v_fmac_f32_e32 v107, v91, v6
	v_fmac_f32_e32 v52, v91, v31
	v_fmac_f32_e32 v53, v91, v28
	v_fmac_f32_e32 v50, v91, v29
	v_fmac_f32_e32 v51, v91, v26
	v_fmac_f32_e32 v48, v91, v27
	v_fmac_f32_e32 v49, v91, v24
	v_fmac_f32_e32 v46, v91, v25
	v_fmac_f32_e32 v47, v91, v22
	v_fmac_f32_e32 v44, v91, v23
	v_fmac_f32_e32 v45, v91, v20
	v_fmac_f32_e32 v42, v91, v21
	v_fmac_f32_e32 v43, v91, v18
	v_fmac_f32_e32 v40, v91, v19
	v_fmac_f32_e32 v41, v91, v16
	v_fmac_f32_e32 v38, v91, v17
	v_fmac_f32_e32 v39, v91, v14
	v_fmac_f32_e32 v36, v91, v15
	v_fmac_f32_e32 v37, v91, v12
	v_fmac_f32_e32 v34, v91, v13
	v_fmac_f32_e32 v35, v91, v10
	v_fmac_f32_e32 v32, v104, v9
	v_fmac_f32_e32 v33, v104, v6
	v_fmac_f32_e32 v30, v104, v7
	v_fmac_f32_e32 v107, v106, v7
	v_fmac_f32_e32 v56, v100, v31
	v_fmac_f32_e32 v57, v102, v31
	v_fmac_f32_e32 v54, v104, v31
	v_fmac_f32_e32 v55, v106, v31
	v_fmac_f32_e32 v52, v106, v28
	v_fmac_f32_e32 v53, v106, v29
	v_fmac_f32_e32 v50, v106, v26
	v_fmac_f32_e32 v51, v106, v27
	v_fmac_f32_e32 v48, v106, v24
	v_fmac_f32_e32 v49, v106, v25
	v_fmac_f32_e32 v46, v106, v22
	v_fmac_f32_e32 v47, v106, v23
	v_fmac_f32_e32 v44, v106, v20
	v_fmac_f32_e32 v45, v106, v21
	v_fmac_f32_e32 v42, v106, v18
	v_fmac_f32_e32 v43, v106, v19
	v_fmac_f32_e32 v40, v106, v16
	v_fmac_f32_e32 v41, v106, v17
	v_fmac_f32_e32 v38, v106, v14
	v_fmac_f32_e32 v39, v106, v15
	v_fmac_f32_e32 v36, v106, v12
	v_fmac_f32_e32 v37, v106, v13
	v_fmac_f32_e32 v34, v106, v10
	v_fmac_f32_e32 v35, v106, v11
	v_fmac_f32_e32 v32, v102, v6
	v_fmac_f32_e32 v33, v102, v7
	s_waitcnt lgkmcnt(3)
	v_fmac_f32_e32 v30, v102, v4
	v_fmac_f32_e32 v107, v104, v4
	v_fmac_f32_e32 v56, v98, v28
	v_fmac_f32_e32 v57, v100, v28
	v_fmac_f32_e32 v54, v102, v28
	v_fmac_f32_e32 v55, v104, v28
	v_fmac_f32_e32 v52, v104, v29
	v_fmac_f32_e32 v53, v104, v26
	v_fmac_f32_e32 v50, v104, v27
	v_fmac_f32_e32 v51, v104, v24
	v_fmac_f32_e32 v48, v104, v25
	v_fmac_f32_e32 v49, v104, v22
	v_fmac_f32_e32 v46, v104, v23
	v_fmac_f32_e32 v47, v104, v20
	v_fmac_f32_e32 v44, v104, v21
	v_fmac_f32_e32 v45, v104, v18
	v_fmac_f32_e32 v42, v104, v19
	v_fmac_f32_e32 v43, v104, v16
	v_fmac_f32_e32 v40, v104, v17
	v_fmac_f32_e32 v41, v104, v14
	v_fmac_f32_e32 v38, v104, v15
	v_fmac_f32_e32 v39, v104, v12
	v_fmac_f32_e32 v36, v104, v13
	v_fmac_f32_e32 v37, v104, v10
	v_fmac_f32_e32 v34, v104, v11
	v_fmac_f32_e32 v35, v104, v8
	v_fmac_f32_e32 v32, v100, v7
	v_fmac_f32_e32 v33, v100, v4
	v_fmac_f32_e32 v30, v100, v5
	v_fmac_f32_e32 v107, v102, v5
	v_fmac_f32_e32 v56, v96, v29
	v_fmac_f32_e32 v57, v98, v29
	v_fmac_f32_e32 v54, v100, v29
	v_fmac_f32_e32 v55, v102, v29
	v_fmac_f32_e32 v52, v102, v26
	v_fmac_f32_e32 v53, v102, v27
	v_fmac_f32_e32 v50, v102, v24
	v_fmac_f32_e32 v51, v102, v25
	v_fmac_f32_e32 v48, v102, v22
	v_fmac_f32_e32 v49, v102, v23
	v_fmac_f32_e32 v46, v102, v20
	v_fmac_f32_e32 v47, v102, v21
	v_fmac_f32_e32 v44, v102, v18
	v_fmac_f32_e32 v45, v102, v19
	v_fmac_f32_e32 v42, v102, v16
	v_fmac_f32_e32 v43, v102, v17
	v_fmac_f32_e32 v40, v102, v14
	v_fmac_f32_e32 v41, v102, v15
	v_fmac_f32_e32 v38, v102, v12
	v_fmac_f32_e32 v39, v102, v13
	v_fmac_f32_e32 v36, v102, v10
	v_fmac_f32_e32 v37, v102, v11
	v_fmac_f32_e32 v34, v102, v8
	v_fmac_f32_e32 v35, v102, v9
	v_fmac_f32_e32 v32, v98, v4
	v_fmac_f32_e32 v33, v98, v5
	s_waitcnt lgkmcnt(2)
	v_fmac_f32_e32 v30, v98, v2
	v_fmac_f32_e32 v107, v100, v2
	v_fmac_f32_e32 v56, v94, v26
	v_fmac_f32_e32 v57, v96, v26
	v_fmac_f32_e32 v54, v98, v26
	v_fmac_f32_e32 v55, v100, v26
	v_fmac_f32_e32 v52, v100, v27
	v_fmac_f32_e32 v53, v100, v24
	v_fmac_f32_e32 v50, v100, v25
	v_fmac_f32_e32 v51, v100, v22
	v_fmac_f32_e32 v48, v100, v23
	v_fmac_f32_e32 v49, v100, v20
	v_fmac_f32_e32 v46, v100, v21
	v_fmac_f32_e32 v47, v100, v18
	v_fmac_f32_e32 v44, v100, v19
	v_fmac_f32_e32 v45, v100, v16
	v_fmac_f32_e32 v42, v100, v17
	v_fmac_f32_e32 v43, v100, v14
	v_fmac_f32_e32 v40, v100, v15
	v_fmac_f32_e32 v41, v100, v12
	v_fmac_f32_e32 v38, v100, v13
	v_fmac_f32_e32 v39, v100, v10
	v_fmac_f32_e32 v36, v100, v11
	v_fmac_f32_e32 v37, v100, v8
	v_fmac_f32_e32 v34, v100, v9
	v_fmac_f32_e32 v35, v100, v6
	v_fmac_f32_e32 v32, v96, v5
	v_fmac_f32_e32 v33, v96, v2
	v_fmac_f32_e32 v30, v96, v3
	v_fmac_f32_e32 v107, v98, v3
	v_and_b32_e32 v26, 63, v68
	v_fmac_f32_e32 v109, v98, v31
	v_fmac_f32_e32 v55, v98, v27
	v_fmac_f32_e32 v52, v98, v24
	v_fmac_f32_e32 v53, v98, v25
	v_fmac_f32_e32 v50, v98, v22
	v_fmac_f32_e32 v51, v98, v23
	v_fmac_f32_e32 v48, v98, v20
	v_fmac_f32_e32 v49, v98, v21
	v_fmac_f32_e32 v46, v98, v18
	v_fmac_f32_e32 v47, v98, v19
	v_fmac_f32_e32 v44, v98, v16
	v_fmac_f32_e32 v45, v98, v17
	v_fmac_f32_e32 v42, v98, v14
	v_fmac_f32_e32 v43, v98, v15
	v_fmac_f32_e32 v40, v98, v12
	v_fmac_f32_e32 v41, v98, v13
	v_fmac_f32_e32 v38, v98, v10
	v_fmac_f32_e32 v39, v98, v11
	v_fmac_f32_e32 v36, v98, v8
	v_fmac_f32_e32 v37, v98, v9
	v_fmac_f32_e32 v34, v98, v6
	v_fmac_f32_e32 v35, v98, v7
	v_fmac_f32_e32 v32, v94, v2
	v_fmac_f32_e32 v33, v94, v3
	s_waitcnt lgkmcnt(1)
; DI void mixer_tile(unsigned char* smem_, const Params& p, int layer, const bf16_t* __restrict__ proj, bf16_t* __restrict__ y, int tile_) {
;     ...
;             for (int k = 0; k < 31; ++k) a += w[k] * u[t + k];
;             U[t * 256 + tid] = a;
;         }
;     }
;     __syncthreads();
;     {
;         const f32x4 g4 = *(const f32x4*)(p.in[4] + layer * 256 + 4 * lane), b4 = *(const f32x4*)(p.in[5] + layer * 256 + 4 * lane);
; #pragma unroll
;         for (int tt = 0; tt < 8; ++tt) {
;             const int t = wid * 8 + tt;
;             const f32x4 v = *(const f32x4*)(U + t * 256 + 4 * lane);
;             const float mean = wave_sum((v.x + v.y) + (v.z + v.w)) * (1.f / 256.f);
;             const float dx = v.x - mean, dy = v.y - mean, dz = v.z - mean, dw = v.w - mean;
;             const float var = wave_sum((dx * dx + dy * dy) + (dz * dz + dw * dw)) * (1.f / 256.f);
	v_fmac_f32_e32 v30, v94, v0
	v_fmac_f32_e32 v107, v96, v0
	v_lshlrev_b32_e32 v0, 4, v26
	v_fmac_f32_e32 v108, v96, v31
	v_fmac_f32_e32 v109, v96, v28
	v_fmac_f32_e32 v54, v96, v27
	v_fmac_f32_e32 v55, v96, v24
	v_fmac_f32_e32 v52, v96, v25
	v_fmac_f32_e32 v53, v96, v22
	v_fmac_f32_e32 v50, v96, v23
	v_fmac_f32_e32 v51, v96, v20
	v_fmac_f32_e32 v48, v96, v21
	v_fmac_f32_e32 v49, v96, v18
	v_fmac_f32_e32 v46, v96, v19
	v_fmac_f32_e32 v47, v96, v16
	v_fmac_f32_e32 v44, v96, v17
	v_fmac_f32_e32 v45, v96, v14
	v_fmac_f32_e32 v42, v96, v15
	v_fmac_f32_e32 v43, v96, v12
	v_fmac_f32_e32 v40, v96, v13
	v_fmac_f32_e32 v41, v96, v10
	v_fmac_f32_e32 v38, v96, v11
	v_fmac_f32_e32 v39, v96, v8
	v_fmac_f32_e32 v36, v96, v9
	v_fmac_f32_e32 v37, v96, v6
	v_fmac_f32_e32 v34, v96, v7
	v_fmac_f32_e32 v35, v96, v4
	ds_write2st64_b32 v72, v32, v33 offset0:112 offset1:116
	v_add_u32_e32 v32, s19, v0
	v_fmac_f32_e32 v108, v94, v28
	v_fmac_f32_e32 v109, v94, v29
	v_fmac_f32_e32 v57, v94, v27
	v_fmac_f32_e32 v54, v94, v24
	v_fmac_f32_e32 v55, v94, v25
	v_fmac_f32_e32 v52, v94, v22
	v_fmac_f32_e32 v53, v94, v23
	v_fmac_f32_e32 v50, v94, v20
	v_fmac_f32_e32 v51, v94, v21
	v_fmac_f32_e32 v48, v94, v18
	v_fmac_f32_e32 v49, v94, v19
	v_fmac_f32_e32 v46, v94, v16
	v_fmac_f32_e32 v47, v94, v17
	v_fmac_f32_e32 v44, v94, v14
	v_fmac_f32_e32 v45, v94, v15
	v_fmac_f32_e32 v42, v94, v12
	v_fmac_f32_e32 v43, v94, v13
	v_fmac_f32_e32 v40, v94, v10
	v_fmac_f32_e32 v41, v94, v11
	v_fmac_f32_e32 v38, v94, v8
	v_fmac_f32_e32 v39, v94, v9
	v_fmac_f32_e32 v36, v94, v6
	v_fmac_f32_e32 v37, v94, v7
	v_fmac_f32_e32 v34, v94, v4
	v_fmac_f32_e32 v35, v94, v5
	v_fmac_f32_e32 v107, v94, v1
	v_lshl_add_u32 v12, s2, 10, v32
	v_lshl_add_u32 v20, s3, 10, v32
	ds_write2st64_b32 v72, v108, v109 offset0:8 offset1:12
	ds_write2st64_b32 v72, v56, v57 offset0:16 offset1:20
	ds_write2st64_b32 v72, v54, v55 offset0:24 offset1:28
	ds_write2st64_b32 v72, v52, v53 offset0:32 offset1:36
	ds_write2st64_b32 v72, v50, v51 offset0:40 offset1:44
	ds_write2st64_b32 v72, v48, v49 offset0:48 offset1:52
	ds_write2st64_b32 v72, v46, v47 offset0:56 offset1:60
	ds_write2st64_b32 v72, v44, v45 offset0:64 offset1:68
	ds_write2st64_b32 v72, v42, v43 offset0:72 offset1:76
	ds_write2st64_b32 v72, v40, v41 offset0:80 offset1:84
	ds_write2st64_b32 v72, v38, v39 offset0:88 offset1:92
	ds_write2st64_b32 v72, v36, v37 offset0:96 offset1:100
	ds_write2st64_b32 v72, v34, v35 offset0:104 offset1:108
	ds_write2st64_b32 v72, v30, v107 offset0:120 offset1:124
	s_waitcnt lgkmcnt(0)
	s_barrier
	global_load_dwordx4 v[2:5], v0, s[8:9]
	global_load_dwordx4 v[6:9], v0, s[10:11]
	ds_read_b128 v[12:15], v12
	ds_read_b128 v[22:25], v20
	v_cndmask_b32_e32 v1, v197, v204, vcc
	v_lshlrev_b32_e32 v31, 2, v1
	v_cmp_lt_i32_e32 vcc, v203, v200
	s_waitcnt lgkmcnt(1)
	v_mov_b32_e32 v16, v13
	v_mov_b32_e32 v17, v14
	v_mov_b32_e32 v18, v12
	v_mov_b32_e32 v19, v15
	s_waitcnt lgkmcnt(0)
	v_mov_b32_e32 v20, v23
	v_mov_b32_e32 v21, v24
	v_mov_b32_e32 v34, v22
	v_mov_b32_e32 v35, v25
	v_pk_add_f32 v[16:17], v[16:17], v[18:19]
	v_pk_add_f32 v[20:21], v[20:21], v[34:35]
	v_add_f32_e32 v16, v16, v17
	v_add_f32_e32 v20, v20, v21
	ds_bpermute_b32 v17, v31, v16
	ds_bpermute_b32 v21, v31, v20
	v_cndmask_b32_e32 v1, v197, v203, vcc
	v_lshlrev_b32_e32 v30, 2, v1
	v_cmp_lt_i32_e32 vcc, v202, v200
	s_waitcnt lgkmcnt(1)
	v_add_f32_e32 v16, v16, v17
	s_waitcnt lgkmcnt(0)
	v_add_f32_e32 v20, v20, v21
	ds_bpermute_b32 v17, v30, v16
	ds_bpermute_b32 v21, v30, v20
	v_cndmask_b32_e32 v1, v197, v202, vcc
	v_lshlrev_b32_e32 v29, 2, v1
	v_cmp_lt_i32_e32 vcc, v201, v200
	s_waitcnt lgkmcnt(1)
	v_add_f32_e32 v16, v16, v17
	s_waitcnt lgkmcnt(0)
	v_add_f32_e32 v20, v20, v21
	ds_bpermute_b32 v17, v29, v16
	ds_bpermute_b32 v21, v29, v20
	v_cndmask_b32_e32 v1, v197, v201, vcc
	v_lshlrev_b32_e32 v28, 2, v1
	v_cmp_lt_i32_e32 vcc, v199, v200
	s_waitcnt lgkmcnt(1)
	v_add_f32_e32 v16, v16, v17
	s_waitcnt lgkmcnt(0)
	v_add_f32_e32 v20, v20, v21
	ds_bpermute_b32 v17, v28, v16
	ds_bpermute_b32 v21, v28, v20
	v_cndmask_b32_e32 v1, v197, v199, vcc
	v_lshlrev_b32_e32 v27, 2, v1
	v_cmp_lt_i32_e32 vcc, v205, v200
	s_waitcnt lgkmcnt(1)
	v_add_f32_e32 v16, v16, v17
	s_waitcnt lgkmcnt(0)
	v_add_f32_e32 v20, v20, v21
	ds_bpermute_b32 v17, v27, v16
	ds_bpermute_b32 v21, v27, v20
	v_cndmask_b32_e32 v1, v197, v205, vcc
	v_lshlrev_b32_e32 v1, 2, v1
	v_lshlrev_b32_e32 v128, 3, v26
	s_waitcnt lgkmcnt(1)
	v_add_f32_e32 v16, v16, v17
	s_waitcnt lgkmcnt(0)
	v_add_f32_e32 v20, v20, v21
	ds_bpermute_b32 v17, v1, v16
	ds_bpermute_b32 v21, v1, v20
	v_lshl_add_u64 v[10:11], s[88:89], 0, v[128:129]
	v_mov_b32_e32 v0, 0
	v_lshlrev_b32_e32 v128, 1, v92
	s_waitcnt lgkmcnt(1)
	v_add_f32_e32 v16, v16, v17
	s_waitcnt lgkmcnt(0)
	v_add_f32_e32 v20, v20, v21
	v_mul_f32_e32 v18, 0x3b800000, v16
	v_mul_f32_e32 v34, 0x3b800000, v20
	v_pk_add_f32 v[16:17], v[14:15], v[18:19] op_sel_hi:[1,0] neg_lo:[0,1] neg_hi:[0,1]
	v_pk_add_f32 v[18:19], v[12:13], v[18:19] op_sel_hi:[1,0] neg_lo:[0,1] neg_hi:[0,1]
	v_pk_add_f32 v[20:21], v[24:25], v[34:35] op_sel_hi:[1,0] neg_lo:[0,1] neg_hi:[0,1]
	v_pk_add_f32 v[22:23], v[22:23], v[34:35] op_sel_hi:[1,0] neg_lo:[0,1] neg_hi:[0,1]
	v_mov_b32_e32 v14, v19
	v_mov_b32_e32 v15, v17
	v_mov_b32_e32 v34, v23
	v_mov_b32_e32 v35, v21
	v_mov_b32_e32 v12, v18
	v_mov_b32_e32 v13, v16
	v_pk_mul_f32 v[14:15], v[14:15], v[14:15]
	v_mov_b32_e32 v24, v22
	v_mov_b32_e32 v25, v20
	v_pk_mul_f32 v[34:35], v[34:35], v[34:35]
	v_pk_fma_f32 v[12:13], v[12:13], v[12:13], v[14:15]
	v_pk_fma_f32 v[24:25], v[24:25], v[24:25], v[34:35]
	v_mov_b32_e32 v35, v12
	v_mov_b32_e32 v34, v24
	v_mov_b32_e32 v12, v25
	v_pk_add_f32 v[12:13], v[34:35], v[12:13]
	ds_bpermute_b32 v25, v31, v13
	ds_bpermute_b32 v24, v31, v12
	v_lshl_add_u64 v[14:15], v[10:11], 0, s[0:1]
	s_mov_b32 s0, 0x3727c5ac
	s_waitcnt lgkmcnt(0)
; DI unsigned pk2(float lo, float hi) { const f32x2 v = {lo, hi}; return __builtin_bit_cast(unsigned, __builtin_convertvector(v, bf16x2_t)); }
; DI void mixer_tile(unsigned char* smem_, const Params& p, int layer, const bf16_t* __restrict__ proj, bf16_t* __restrict__ y, int tile_) {
;     ...
;             const float mean = wave_sum((v.x + v.y) + (v.z + v.w)) * (1.f / 256.f);
;             const float dx = v.x - mean, dy = v.y - mean, dz = v.z - mean, dw = v.w - mean;
;             const float var = wave_sum((dx * dx + dy * dy) + (dz * dz + dw * dw)) * (1.f / 256.f);
;             const float rstd = rsqrtf(var + LN_EPS);
;             float o0 = dx * rstd * g4.x + b4.x, o1 = dy * rstd * g4.y + b4.y, o2 = dz * rstd * g4.z + b4.z, o3 = dw * rstd * g4.w + b4.w;
;             o0 = o0 / (1.f + __expf(-o0)); o1 = o1 / (1.f + __expf(-o1)); o2 = o2 / (1.f + __expf(-o2)); o3 = o3 / (1.f + __expf(-o3));
;             u32x2 wv; wv.x = pk2(o0, o1); wv.y = pk2(o2, o3);
;             *(u32x2*)(y + (size_t)(tok0 + t) * PA + 4 * lane) = wv;
	v_pk_add_f32 v[12:13], v[12:13], v[24:25]
	ds_bpermute_b32 v25, v30, v13
	ds_bpermute_b32 v24, v30, v12
	s_waitcnt lgkmcnt(0)
	v_pk_add_f32 v[12:13], v[12:13], v[24:25]
	ds_bpermute_b32 v25, v29, v13
	ds_bpermute_b32 v24, v29, v12
	s_waitcnt lgkmcnt(0)
	v_pk_add_f32 v[12:13], v[12:13], v[24:25]
	ds_bpermute_b32 v25, v28, v13
	ds_bpermute_b32 v24, v28, v12
	s_waitcnt lgkmcnt(0)
	v_pk_add_f32 v[12:13], v[12:13], v[24:25]
	ds_bpermute_b32 v25, v27, v13
	ds_bpermute_b32 v24, v27, v12
	s_waitcnt lgkmcnt(0)
	v_pk_add_f32 v[12:13], v[12:13], v[24:25]
	ds_bpermute_b32 v25, v1, v13
	ds_bpermute_b32 v24, v1, v12
	s_waitcnt lgkmcnt(0)
	v_pk_add_f32 v[24:25], v[12:13], v[24:25]
	v_mov_b64_e32 v[12:13], s[0:1]
	v_pk_fma_f32 v[24:25], v[24:25], s[22:23], v[12:13] op_sel_hi:[1,0,0]
	s_nop 0
	v_mul_f32_e32 v33, 0x4b800000, v25
	v_cmp_gt_f32_e32 vcc, s69, v25
	v_cmp_gt_f32_e64 s[0:1], s69, v24
	s_nop 0
	v_cndmask_b32_e32 v25, v25, v33, vcc
	v_rsq_f32_e32 v25, v25
	s_nop 0
	v_mul_f32_e32 v33, 0x45800000, v25
	v_cndmask_b32_e32 v34, v25, v33, vcc
	v_pk_mul_f32 v[18:19], v[18:19], v[34:35] op_sel_hi:[1,0]
	v_pk_mul_f32 v[16:17], v[16:17], v[34:35] op_sel_hi:[1,0]
	s_waitcnt vmcnt(0)
	v_pk_fma_f32 v[18:19], v[2:3], v[18:19], v[6:7]
	v_pk_fma_f32 v[16:17], v[4:5], v[16:17], v[8:9]
	v_mul_f32_e32 v25, 0xbfb8aa3b, v18
	v_exp_f32_e32 v34, v25
	v_mul_f32_e32 v25, 0xbfb8aa3b, v19
	v_exp_f32_e32 v35, v25
	s_nop 0
	v_pk_add_f32 v[34:35], v[34:35], 1.0 op_sel_hi:[1,0]
	s_nop 0
	v_div_scale_f32 v25, s[20:21], v35, v35, v19
	v_rcp_f32_e32 v33, v25
	s_nop 0
	v_fma_f32 v36, -v25, v33, 1.0
	v_fmac_f32_e32 v33, v36, v33
	v_div_scale_f32 v36, vcc, v19, v35, v19
	v_mul_f32_e32 v37, v36, v33
	v_fma_f32 v38, -v25, v37, v36
	v_fmac_f32_e32 v37, v38, v33
	v_fma_f32 v25, -v25, v37, v36
	v_div_fmas_f32 v25, v25, v33, v37
	v_div_fixup_f32 v25, v25, v35, v19
	v_div_scale_f32 v19, s[20:21], v34, v34, v18
	v_rcp_f32_e32 v33, v19
	s_nop 0
	v_fma_f32 v35, -v19, v33, 1.0
	v_fmac_f32_e32 v33, v35, v33
	v_div_scale_f32 v35, vcc, v18, v34, v18
	v_mul_f32_e32 v36, v35, v33
	v_fma_f32 v37, -v19, v36, v35
	v_fmac_f32_e32 v36, v37, v33
	v_fma_f32 v19, -v19, v36, v35
	v_div_fmas_f32 v19, v19, v33, v36
	v_div_fixup_f32 v33, v19, v34, v18
	v_mul_f32_e32 v18, 0xbfb8aa3b, v16
	v_mul_f32_e32 v19, 0xbfb8aa3b, v17
	v_exp_f32_e32 v18, v18
	v_exp_f32_e32 v19, v19
	s_nop 0
	v_pk_add_f32 v[18:19], v[18:19], 1.0 op_sel_hi:[1,0]
	s_nop 0
	v_div_scale_f32 v34, s[20:21], v19, v19, v17
	v_rcp_f32_e32 v35, v34
	s_nop 0
	v_fma_f32 v36, -v34, v35, 1.0
	v_fmac_f32_e32 v35, v36, v35
	v_div_scale_f32 v36, vcc, v17, v19, v17
	v_mul_f32_e32 v37, v36, v35
	v_fma_f32 v38, -v34, v37, v36
	v_fmac_f32_e32 v37, v38, v35
	v_fma_f32 v34, -v34, v37, v36
	v_div_fmas_f32 v34, v34, v35, v37
	v_div_fixup_f32 v17, v34, v19, v17
	v_div_scale_f32 v19, s[20:21], v18, v18, v16
	v_rcp_f32_e32 v34, v19
	s_nop 0
	v_fma_f32 v35, -v19, v34, 1.0
	v_fmac_f32_e32 v34, v35, v34
	v_div_scale_f32 v35, vcc, v16, v18, v16
	v_mul_f32_e32 v36, v35, v34
	v_fma_f32 v37, -v19, v36, v35
	v_fmac_f32_e32 v36, v37, v34
	v_fma_f32 v19, -v19, v36, v35
	v_div_fmas_f32 v19, v19, v34, v36
	v_div_fixup_f32 v18, v19, v18, v16
	v_cvt_pk_bf16_f32 v16, v33, v25
	v_cvt_pk_bf16_f32 v17, v18, v17
	global_store_dwordx2 v[14:15], v[16:17], off
	v_mul_f32_e32 v14, 0x4b800000, v24
	v_cndmask_b32_e64 v14, v24, v14, s[0:1]
	v_rsq_f32_e32 v14, v14
	s_nop 0
	v_mul_f32_e32 v15, 0x45800000, v14
	v_cndmask_b32_e64 v14, v14, v15, s[0:1]
	v_pk_mul_f32 v[16:17], v[22:23], v[14:15] op_sel_hi:[1,0]
	v_pk_mul_f32 v[14:15], v[20:21], v[14:15] op_sel_hi:[1,0]
	v_pk_fma_f32 v[16:17], v[2:3], v[16:17], v[6:7]
	v_pk_fma_f32 v[14:15], v[4:5], v[14:15], v[8:9]
	v_mul_f32_e32 v18, 0xbfb8aa3b, v16
	v_mul_f32_e32 v19, 0xbfb8aa3b, v17
	v_exp_f32_e32 v18, v18
	v_exp_f32_e32 v19, v19
	s_nop 0
	v_pk_add_f32 v[18:19], v[18:19], 1.0 op_sel_hi:[1,0]
	s_nop 0
	v_div_scale_f32 v20, s[0:1], v19, v19, v17
	v_rcp_f32_e32 v21, v20
	s_nop 0
	v_fma_f32 v22, -v20, v21, 1.0
	v_fmac_f32_e32 v21, v22, v21
	v_div_scale_f32 v22, vcc, v17, v19, v17
	v_mul_f32_e32 v23, v22, v21
	v_fma_f32 v24, -v20, v23, v22
	v_fmac_f32_e32 v23, v24, v21
	v_fma_f32 v20, -v20, v23, v22
	v_div_fmas_f32 v20, v20, v21, v23
	v_div_fixup_f32 v19, v20, v19, v17
	v_div_scale_f32 v17, s[0:1], v18, v18, v16
	v_rcp_f32_e32 v20, v17
	s_nop 0
	v_fma_f32 v21, -v17, v20, 1.0
	v_fmac_f32_e32 v20, v21, v20
	v_div_scale_f32 v21, vcc, v16, v18, v16
	v_mul_f32_e32 v22, v21, v20
	v_fma_f32 v23, -v17, v22, v21
	v_fmac_f32_e32 v22, v23, v20
	v_fma_f32 v17, -v17, v22, v21
	v_div_fmas_f32 v17, v17, v20, v22
	v_div_fixup_f32 v18, v17, v18, v16
	v_mul_f32_e32 v16, 0xbfb8aa3b, v14
	v_mul_f32_e32 v17, 0xbfb8aa3b, v15
	v_exp_f32_e32 v16, v16
	v_exp_f32_e32 v17, v17
	s_nop 0
	v_pk_add_f32 v[16:17], v[16:17], 1.0 op_sel_hi:[1,0]
	s_nop 0
	v_div_scale_f32 v20, s[0:1], v17, v17, v15
	v_rcp_f32_e32 v21, v20
	s_nop 0
	v_fma_f32 v22, -v20, v21, 1.0
	v_fmac_f32_e32 v21, v22, v21
	v_div_scale_f32 v22, vcc, v15, v17, v15
	v_mul_f32_e32 v23, v22, v21
	v_fma_f32 v24, -v20, v23, v22
	v_fmac_f32_e32 v23, v24, v21
	v_fma_f32 v20, -v20, v23, v22
	v_div_fmas_f32 v20, v20, v21, v23
	v_div_fixup_f32 v15, v20, v17, v15
	v_div_scale_f32 v17, s[0:1], v16, v16, v14
	v_rcp_f32_e32 v20, v17
	s_or_b32 s0, s3, s17
	s_ashr_i32 s1, s0, 31
	s_lshl_b64 s[0:1], s[0:1], 11
	v_fma_f32 v21, -v17, v20, 1.0
	v_fmac_f32_e32 v20, v21, v20
	v_div_scale_f32 v21, vcc, v14, v16, v14
	v_mul_f32_e32 v22, v21, v20
	v_fma_f32 v23, -v17, v22, v21
	v_fmac_f32_e32 v22, v23, v20
	v_fma_f32 v17, -v17, v22, v21
	v_div_fmas_f32 v17, v17, v20, v22
	v_div_fixup_f32 v16, v17, v16, v14
	v_cvt_pk_bf16_f32 v14, v18, v19
	v_cvt_pk_bf16_f32 v15, v16, v15
	v_lshl_add_u64 v[16:17], v[10:11], 0, s[0:1]
	s_or_b32 s0, s2, 2
	global_store_dwordx2 v[16:17], v[14:15], off
	v_lshl_add_u32 v14, s0, 10, v32
	ds_read_b128 v[14:17], v14
	s_or_b32 s3, s2, 3
	s_or_b32 s0, s0, s17
	s_ashr_i32 s1, s0, 31
	s_lshl_b64 s[0:1], s[0:1], 11
	s_waitcnt lgkmcnt(0)
; DI void mixer_tile(unsigned char* smem_, const Params& p, int layer, const bf16_t* __restrict__ proj, bf16_t* __restrict__ y, int tile_) {
;     ...
;         for (int tt = 0; tt < 8; ++tt) {
;             const int t = wid * 8 + tt;
;             const f32x4 v = *(const f32x4*)(U + t * 256 + 4 * lane);
;             const float mean = wave_sum((v.x + v.y) + (v.z + v.w)) * (1.f / 256.f);
;             const float dx = v.x - mean, dy = v.y - mean, dz = v.z - mean, dw = v.w - mean;
;             const float var = wave_sum((dx * dx + dy * dy) + (dz * dz + dw * dw)) * (1.f / 256.f);
;             const float rstd = rsqrtf(var + LN_EPS);
;             float o0 = dx * rstd * g4.x + b4.x, o1 = dy * rstd * g4.y + b4.y, o2 = dz * rstd * g4.z + b4.z, o3 = dw * rstd * g4.w + b4.w;
;             o0 = o0 / (1.f + __expf(-o0)); o1 = o1 / (1.f + __expf(-o1)); o2 = o2 / (1.f + __expf(-o2)); o3 = o3 / (1.f + __expf(-o3));
	v_mov_b32_e32 v18, v15
	v_mov_b32_e32 v19, v16
	v_mov_b32_e32 v20, v14
	v_mov_b32_e32 v21, v17
	v_pk_add_f32 v[18:19], v[18:19], v[20:21]
	s_nop 0
	v_add_f32_e32 v18, v18, v19
	s_waitcnt lgkmcnt(0)
	s_nop 1
	v_add_f32_dpp v18, v18, v18 quad_perm:[1,0,3,2] row_mask:0xf bank_mask:0xf
	s_nop 1
	v_add_f32_dpp v18, v18, v18 quad_perm:[2,3,0,1] row_mask:0xf bank_mask:0xf
	s_nop 1
	v_add_f32_dpp v18, v18, v18 row_half_mirror row_mask:0xf bank_mask:0xf
	s_nop 1
	v_add_f32_dpp v18, v18, v18 row_mirror row_mask:0xf bank_mask:0xf
	s_nop 1
	v_add_f32_dpp v18, v18, v18 row_bcast:15 row_mask:0xa bank_mask:0xf
	s_nop 1
	v_add_f32_dpp v18, v18, v18 row_bcast:31 row_mask:0xc bank_mask:0xf
	s_nop 0
	v_readlane_b32 vcc_lo, v18, 63
	s_nop 1
	v_mov_b32_e32 v18, vcc_lo
	v_mul_f32_e32 v18, 0x3b800000, v18
	v_pk_add_f32 v[16:17], v[16:17], v[18:19] op_sel_hi:[1,0] neg_lo:[0,1] neg_hi:[0,1]
	v_pk_add_f32 v[18:19], v[14:15], v[18:19] op_sel_hi:[1,0] neg_lo:[0,1] neg_hi:[0,1]
	v_mov_b32_e32 v21, v17
	v_mov_b32_e32 v20, v19
	v_mov_b32_e32 v14, v18
	v_mov_b32_e32 v15, v16
	v_pk_mul_f32 v[20:21], v[20:21], v[20:21]
	s_nop 0
	v_pk_fma_f32 v[24:25], v[14:15], v[14:15], v[20:21]
	v_lshl_add_u32 v20, s3, 10, v32
	ds_read_b128 v[34:37], v20
	v_lshl_add_u64 v[14:15], v[10:11], 0, s[0:1]
	s_waitcnt lgkmcnt(0)
	v_mov_b32_e32 v20, v35
	v_mov_b32_e32 v21, v36
	v_mov_b32_e32 v22, v34
	v_mov_b32_e32 v23, v37
	v_pk_add_f32 v[20:21], v[20:21], v[22:23]
	s_nop 0
	v_add_f32_e32 v20, v20, v21
	s_waitcnt lgkmcnt(0)
	s_nop 1
	v_add_f32_dpp v20, v20, v20 quad_perm:[1,0,3,2] row_mask:0xf bank_mask:0xf
	s_nop 1
	v_add_f32_dpp v20, v20, v20 quad_perm:[2,3,0,1] row_mask:0xf bank_mask:0xf
	s_nop 1
	v_add_f32_dpp v20, v20, v20 row_half_mirror row_mask:0xf bank_mask:0xf
	s_nop 1
	v_add_f32_dpp v20, v20, v20 row_mirror row_mask:0xf bank_mask:0xf
	s_nop 1
	v_add_f32_dpp v20, v20, v20 row_bcast:15 row_mask:0xa bank_mask:0xf
	s_nop 1
	v_add_f32_dpp v20, v20, v20 row_bcast:31 row_mask:0xc bank_mask:0xf
	s_nop 0
	v_readlane_b32 vcc_lo, v20, 63
	s_nop 1
	v_mov_b32_e32 v20, vcc_lo
	v_mul_f32_e32 v22, 0x3b800000, v20
	v_pk_add_f32 v[20:21], v[36:37], v[22:23] op_sel_hi:[1,0] neg_lo:[0,1] neg_hi:[0,1]
	v_pk_add_f32 v[22:23], v[34:35], v[22:23] op_sel_hi:[1,0] neg_lo:[0,1] neg_hi:[0,1]
	v_mov_b32_e32 v37, v21
	v_mov_b32_e32 v36, v23
	v_mov_b32_e32 v34, v22
	v_mov_b32_e32 v35, v20
	v_pk_mul_f32 v[36:37], v[36:37], v[36:37]
	s_nop 0
	v_pk_fma_f32 v[34:35], v[34:35], v[34:35], v[36:37]
	v_mov_b32_e32 v37, v24
	v_mov_b32_e32 v36, v34
	v_mov_b32_e32 v24, v35
	v_pk_add_f32 v[24:25], v[36:37], v[24:25]
	ds_bpermute_b32 v35, v31, v25
	ds_bpermute_b32 v34, v31, v24
	s_waitcnt lgkmcnt(0)
	v_pk_add_f32 v[24:25], v[24:25], v[34:35]
	ds_bpermute_b32 v35, v30, v25
	ds_bpermute_b32 v34, v30, v24
	s_waitcnt lgkmcnt(0)
	v_pk_add_f32 v[24:25], v[24:25], v[34:35]
	ds_bpermute_b32 v35, v29, v25
	ds_bpermute_b32 v34, v29, v24
	s_waitcnt lgkmcnt(0)
	v_pk_add_f32 v[24:25], v[24:25], v[34:35]
	ds_bpermute_b32 v35, v28, v25
	ds_bpermute_b32 v34, v28, v24
	s_waitcnt lgkmcnt(0)
	v_pk_add_f32 v[24:25], v[24:25], v[34:35]
	ds_bpermute_b32 v35, v27, v25
	ds_bpermute_b32 v34, v27, v24
	s_waitcnt lgkmcnt(0)
	v_pk_add_f32 v[24:25], v[24:25], v[34:35]
	ds_bpermute_b32 v35, v1, v25
	ds_bpermute_b32 v34, v1, v24
	s_waitcnt lgkmcnt(0)
	v_pk_add_f32 v[24:25], v[24:25], v[34:35]
	s_nop 0
	v_pk_fma_f32 v[24:25], v[24:25], s[22:23], v[12:13] op_sel_hi:[1,0,0]
	s_nop 0
	v_mul_f32_e32 v33, 0x4b800000, v25
	v_cmp_gt_f32_e32 vcc, s69, v25
	v_cmp_gt_f32_e64 s[0:1], s69, v24
	s_nop 0
	v_cndmask_b32_e32 v25, v25, v33, vcc
	v_rsq_f32_e32 v25, v25
	s_nop 0
	v_mul_f32_e32 v33, 0x45800000, v25
	v_cndmask_b32_e32 v34, v25, v33, vcc
	v_pk_mul_f32 v[18:19], v[18:19], v[34:35] op_sel_hi:[1,0]
	v_pk_mul_f32 v[16:17], v[16:17], v[34:35] op_sel_hi:[1,0]
	v_pk_fma_f32 v[18:19], v[2:3], v[18:19], v[6:7]
	v_pk_fma_f32 v[16:17], v[4:5], v[16:17], v[8:9]
	v_mul_f32_e32 v25, 0xbfb8aa3b, v18
	v_exp_f32_e32 v34, v25
	v_mul_f32_e32 v25, 0xbfb8aa3b, v19
	v_exp_f32_e32 v35, v25
	s_nop 0
	v_pk_add_f32 v[34:35], v[34:35], 1.0 op_sel_hi:[1,0]
	s_nop 0
	v_div_scale_f32 v25, s[20:21], v35, v35, v19
	v_rcp_f32_e32 v33, v25
	s_nop 0
	v_fma_f32 v36, -v25, v33, 1.0
	v_fmac_f32_e32 v33, v36, v33
	v_div_scale_f32 v36, vcc, v19, v35, v19
	v_mul_f32_e32 v37, v36, v33
	v_fma_f32 v38, -v25, v37, v36
	v_fmac_f32_e32 v37, v38, v33
	v_fma_f32 v25, -v25, v37, v36
	v_div_fmas_f32 v25, v25, v33, v37
	v_div_fixup_f32 v25, v25, v35, v19
	v_div_scale_f32 v19, s[20:21], v34, v34, v18
	v_rcp_f32_e32 v33, v19
	s_nop 0
	v_fma_f32 v35, -v19, v33, 1.0
	v_fmac_f32_e32 v33, v35, v33
	v_div_scale_f32 v35, vcc, v18, v34, v18
	v_mul_f32_e32 v36, v35, v33
	v_fma_f32 v37, -v19, v36, v35
	v_fmac_f32_e32 v36, v37, v33
	v_fma_f32 v19, -v19, v36, v35
	v_div_fmas_f32 v19, v19, v33, v36
	v_div_fixup_f32 v33, v19, v34, v18
	v_mul_f32_e32 v18, 0xbfb8aa3b, v16
	v_mul_f32_e32 v19, 0xbfb8aa3b, v17
	v_exp_f32_e32 v18, v18
	v_exp_f32_e32 v19, v19
	s_nop 0
	v_pk_add_f32 v[18:19], v[18:19], 1.0 op_sel_hi:[1,0]
	s_nop 0
	v_div_scale_f32 v34, s[20:21], v19, v19, v17
	v_rcp_f32_e32 v35, v34
	s_nop 0
	v_fma_f32 v36, -v34, v35, 1.0
	v_fmac_f32_e32 v35, v36, v35
	v_div_scale_f32 v36, vcc, v17, v19, v17
	v_mul_f32_e32 v37, v36, v35
	v_fma_f32 v38, -v34, v37, v36
	v_fmac_f32_e32 v37, v38, v35
	v_fma_f32 v34, -v34, v37, v36
	v_div_fmas_f32 v34, v34, v35, v37
	v_div_fixup_f32 v17, v34, v19, v17
	v_div_scale_f32 v19, s[20:21], v18, v18, v16
	v_rcp_f32_e32 v34, v19
	s_nop 0
	v_fma_f32 v35, -v19, v34, 1.0
	v_fmac_f32_e32 v34, v35, v34
	v_div_scale_f32 v35, vcc, v16, v18, v16
	v_mul_f32_e32 v36, v35, v34
	v_fma_f32 v37, -v19, v36, v35
; DI unsigned pk2(float lo, float hi) { const f32x2 v = {lo, hi}; return __builtin_bit_cast(unsigned, __builtin_convertvector(v, bf16x2_t)); }
; DI void mixer_tile(unsigned char* smem_, const Params& p, int layer, const bf16_t* __restrict__ proj, bf16_t* __restrict__ y, int tile_) {
;     ...
;         for (int tt = 0; tt < 8; ++tt) {
;             const int t = wid * 8 + tt;
;             const f32x4 v = *(const f32x4*)(U + t * 256 + 4 * lane);
;             const float mean = wave_sum((v.x + v.y) + (v.z + v.w)) * (1.f / 256.f);
;             const float dx = v.x - mean, dy = v.y - mean, dz = v.z - mean, dw = v.w - mean;
;             const float var = wave_sum((dx * dx + dy * dy) + (dz * dz + dw * dw)) * (1.f / 256.f);
;             const float rstd = rsqrtf(var + LN_EPS);
;             float o0 = dx * rstd * g4.x + b4.x, o1 = dy * rstd * g4.y + b4.y, o2 = dz * rstd * g4.z + b4.z, o3 = dw * rstd * g4.w + b4.w;
;             o0 = o0 / (1.f + __expf(-o0)); o1 = o1 / (1.f + __expf(-o1)); o2 = o2 / (1.f + __expf(-o2)); o3 = o3 / (1.f + __expf(-o3));
;             u32x2 wv; wv.x = pk2(o0, o1); wv.y = pk2(o2, o3);
;             *(u32x2*)(y + (size_t)(tok0 + t) * PA + 4 * lane) = wv;
	v_fmac_f32_e32 v36, v37, v34
	v_fma_f32 v19, -v19, v36, v35
	v_div_fmas_f32 v19, v19, v34, v36
	v_div_fixup_f32 v18, v19, v18, v16
	v_cvt_pk_bf16_f32 v16, v33, v25
	v_cvt_pk_bf16_f32 v17, v18, v17
	global_store_dwordx2 v[14:15], v[16:17], off
	v_mul_f32_e32 v14, 0x4b800000, v24
	v_cndmask_b32_e64 v14, v24, v14, s[0:1]
	v_rsq_f32_e32 v14, v14
	s_nop 0
	v_mul_f32_e32 v15, 0x45800000, v14
	v_cndmask_b32_e64 v14, v14, v15, s[0:1]
	v_pk_mul_f32 v[16:17], v[22:23], v[14:15] op_sel_hi:[1,0]
	v_pk_mul_f32 v[14:15], v[20:21], v[14:15] op_sel_hi:[1,0]
	v_pk_fma_f32 v[16:17], v[2:3], v[16:17], v[6:7]
	v_pk_fma_f32 v[14:15], v[4:5], v[14:15], v[8:9]
	v_mul_f32_e32 v18, 0xbfb8aa3b, v16
	v_mul_f32_e32 v19, 0xbfb8aa3b, v17
	v_exp_f32_e32 v18, v18
	v_exp_f32_e32 v19, v19
	s_nop 0
	v_pk_add_f32 v[18:19], v[18:19], 1.0 op_sel_hi:[1,0]
	s_nop 0
	v_div_scale_f32 v20, s[0:1], v19, v19, v17
	v_rcp_f32_e32 v21, v20
	s_nop 0
	v_fma_f32 v22, -v20, v21, 1.0
	v_fmac_f32_e32 v21, v22, v21
	v_div_scale_f32 v22, vcc, v17, v19, v17
	v_mul_f32_e32 v23, v22, v21
	v_fma_f32 v24, -v20, v23, v22
	v_fmac_f32_e32 v23, v24, v21
	v_fma_f32 v20, -v20, v23, v22
	v_div_fmas_f32 v20, v20, v21, v23
	v_div_fixup_f32 v19, v20, v19, v17
	v_div_scale_f32 v17, s[0:1], v18, v18, v16
	v_rcp_f32_e32 v20, v17
	s_nop 0
	v_fma_f32 v21, -v17, v20, 1.0
	v_fmac_f32_e32 v20, v21, v20
	v_div_scale_f32 v21, vcc, v16, v18, v16
	v_mul_f32_e32 v22, v21, v20
	v_fma_f32 v23, -v17, v22, v21
	v_fmac_f32_e32 v22, v23, v20
	v_fma_f32 v17, -v17, v22, v21
	v_div_fmas_f32 v17, v17, v20, v22
	v_div_fixup_f32 v18, v17, v18, v16
	v_mul_f32_e32 v16, 0xbfb8aa3b, v14
	v_mul_f32_e32 v17, 0xbfb8aa3b, v15
	v_exp_f32_e32 v16, v16
	v_exp_f32_e32 v17, v17
	s_nop 0
	v_pk_add_f32 v[16:17], v[16:17], 1.0 op_sel_hi:[1,0]
	s_nop 0
	v_div_scale_f32 v20, s[0:1], v17, v17, v15
	v_rcp_f32_e32 v21, v20
	s_nop 0
	v_fma_f32 v22, -v20, v21, 1.0
	v_fmac_f32_e32 v21, v22, v21
	v_div_scale_f32 v22, vcc, v15, v17, v15
	v_mul_f32_e32 v23, v22, v21
	v_fma_f32 v24, -v20, v23, v22
	v_fmac_f32_e32 v23, v24, v21
	v_fma_f32 v20, -v20, v23, v22
	v_div_fmas_f32 v20, v20, v21, v23
	v_div_fixup_f32 v15, v20, v17, v15
	v_div_scale_f32 v17, s[0:1], v16, v16, v14
	v_rcp_f32_e32 v20, v17
	s_or_b32 s0, s3, s17
	s_ashr_i32 s1, s0, 31
	s_lshl_b64 s[0:1], s[0:1], 11
	v_fma_f32 v21, -v17, v20, 1.0
	v_fmac_f32_e32 v20, v21, v20
	v_div_scale_f32 v21, vcc, v14, v16, v14
	v_mul_f32_e32 v22, v21, v20
	v_fma_f32 v23, -v17, v22, v21
	v_fmac_f32_e32 v22, v23, v20
	v_fma_f32 v17, -v17, v22, v21
	v_div_fmas_f32 v17, v17, v20, v22
	v_div_fixup_f32 v16, v17, v16, v14
	v_cvt_pk_bf16_f32 v14, v18, v19
	v_cvt_pk_bf16_f32 v15, v16, v15
	v_lshl_add_u64 v[16:17], v[10:11], 0, s[0:1]
	s_or_b32 s0, s2, 4
	global_store_dwordx2 v[16:17], v[14:15], off
	v_lshl_add_u32 v14, s0, 10, v32
	ds_read_b128 v[14:17], v14
	s_or_b32 s3, s2, 5
	s_or_b32 s0, s0, s17
	s_ashr_i32 s1, s0, 31
	s_lshl_b64 s[0:1], s[0:1], 11
	s_waitcnt lgkmcnt(0)
	v_mov_b32_e32 v18, v15
	v_mov_b32_e32 v19, v16
	v_mov_b32_e32 v20, v14
	v_mov_b32_e32 v21, v17
	v_pk_add_f32 v[18:19], v[18:19], v[20:21]
	s_nop 0
	v_add_f32_e32 v18, v18, v19
	s_waitcnt lgkmcnt(0)
	s_nop 1
	v_add_f32_dpp v18, v18, v18 quad_perm:[1,0,3,2] row_mask:0xf bank_mask:0xf
	s_nop 1
	v_add_f32_dpp v18, v18, v18 quad_perm:[2,3,0,1] row_mask:0xf bank_mask:0xf
	s_nop 1
	v_add_f32_dpp v18, v18, v18 row_half_mirror row_mask:0xf bank_mask:0xf
	s_nop 1
	v_add_f32_dpp v18, v18, v18 row_mirror row_mask:0xf bank_mask:0xf
	s_nop 1
	v_add_f32_dpp v18, v18, v18 row_bcast:15 row_mask:0xa bank_mask:0xf
	s_nop 1
	v_add_f32_dpp v18, v18, v18 row_bcast:31 row_mask:0xc bank_mask:0xf
	s_nop 0
	v_readlane_b32 vcc_lo, v18, 63
	s_nop 1
	v_mov_b32_e32 v18, vcc_lo
	v_mul_f32_e32 v18, 0x3b800000, v18
	v_pk_add_f32 v[16:17], v[16:17], v[18:19] op_sel_hi:[1,0] neg_lo:[0,1] neg_hi:[0,1]
	v_pk_add_f32 v[18:19], v[14:15], v[18:19] op_sel_hi:[1,0] neg_lo:[0,1] neg_hi:[0,1]
	v_mov_b32_e32 v21, v17
	v_mov_b32_e32 v20, v19
	v_mov_b32_e32 v14, v18
	v_mov_b32_e32 v15, v16
	v_pk_mul_f32 v[20:21], v[20:21], v[20:21]
	s_nop 0
	v_pk_fma_f32 v[24:25], v[14:15], v[14:15], v[20:21]
	v_lshl_add_u32 v20, s3, 10, v32
	ds_read_b128 v[34:37], v20
	v_lshl_add_u64 v[14:15], v[10:11], 0, s[0:1]
	s_waitcnt lgkmcnt(0)
	v_mov_b32_e32 v20, v35
	v_mov_b32_e32 v21, v36
	v_mov_b32_e32 v22, v34
	v_mov_b32_e32 v23, v37
	v_pk_add_f32 v[20:21], v[20:21], v[22:23]
	s_nop 0
	v_add_f32_e32 v20, v20, v21
	s_waitcnt lgkmcnt(0)
	s_nop 1
	v_add_f32_dpp v20, v20, v20 quad_perm:[1,0,3,2] row_mask:0xf bank_mask:0xf
	s_nop 1
	v_add_f32_dpp v20, v20, v20 quad_perm:[2,3,0,1] row_mask:0xf bank_mask:0xf
	s_nop 1
	v_add_f32_dpp v20, v20, v20 row_half_mirror row_mask:0xf bank_mask:0xf
	s_nop 1
	v_add_f32_dpp v20, v20, v20 row_mirror row_mask:0xf bank_mask:0xf
	s_nop 1
	v_add_f32_dpp v20, v20, v20 row_bcast:15 row_mask:0xa bank_mask:0xf
	s_nop 1
	v_add_f32_dpp v20, v20, v20 row_bcast:31 row_mask:0xc bank_mask:0xf
	s_nop 0
	v_readlane_b32 vcc_lo, v20, 63
	s_nop 1
	v_mov_b32_e32 v20, vcc_lo
	v_mul_f32_e32 v22, 0x3b800000, v20
	v_pk_add_f32 v[20:21], v[36:37], v[22:23] op_sel_hi:[1,0] neg_lo:[0,1] neg_hi:[0,1]
	v_pk_add_f32 v[22:23], v[34:35], v[22:23] op_sel_hi:[1,0] neg_lo:[0,1] neg_hi:[0,1]
	v_mov_b32_e32 v37, v21
	v_mov_b32_e32 v36, v23
	v_mov_b32_e32 v34, v22
	v_mov_b32_e32 v35, v20
	v_pk_mul_f32 v[36:37], v[36:37], v[36:37]
	s_nop 0
	v_pk_fma_f32 v[34:35], v[34:35], v[34:35], v[36:37]
	v_mov_b32_e32 v37, v24
	v_mov_b32_e32 v36, v34
	v_mov_b32_e32 v24, v35
	v_pk_add_f32 v[24:25], v[36:37], v[24:25]
	ds_bpermute_b32 v35, v31, v25
	ds_bpermute_b32 v34, v31, v24
	s_waitcnt lgkmcnt(0)
; DI unsigned pk2(float lo, float hi) { const f32x2 v = {lo, hi}; return __builtin_bit_cast(unsigned, __builtin_convertvector(v, bf16x2_t)); }
; DI void mixer_tile(unsigned char* smem_, const Params& p, int layer, const bf16_t* __restrict__ proj, bf16_t* __restrict__ y, int tile_) {
;     ...
;             const float var = wave_sum((dx * dx + dy * dy) + (dz * dz + dw * dw)) * (1.f / 256.f);
;             const float rstd = rsqrtf(var + LN_EPS);
;             float o0 = dx * rstd * g4.x + b4.x, o1 = dy * rstd * g4.y + b4.y, o2 = dz * rstd * g4.z + b4.z, o3 = dw * rstd * g4.w + b4.w;
;             o0 = o0 / (1.f + __expf(-o0)); o1 = o1 / (1.f + __expf(-o1)); o2 = o2 / (1.f + __expf(-o2)); o3 = o3 / (1.f + __expf(-o3));
;             u32x2 wv; wv.x = pk2(o0, o1); wv.y = pk2(o2, o3);
;             *(u32x2*)(y + (size_t)(tok0 + t) * PA + 4 * lane) = wv;
	v_pk_add_f32 v[24:25], v[24:25], v[34:35]
	ds_bpermute_b32 v35, v30, v25
	ds_bpermute_b32 v34, v30, v24
	s_waitcnt lgkmcnt(0)
	v_pk_add_f32 v[24:25], v[24:25], v[34:35]
	ds_bpermute_b32 v35, v29, v25
	ds_bpermute_b32 v34, v29, v24
	s_waitcnt lgkmcnt(0)
	v_pk_add_f32 v[24:25], v[24:25], v[34:35]
	ds_bpermute_b32 v35, v28, v25
	ds_bpermute_b32 v34, v28, v24
	s_waitcnt lgkmcnt(0)
	v_pk_add_f32 v[24:25], v[24:25], v[34:35]
	ds_bpermute_b32 v35, v27, v25
	ds_bpermute_b32 v34, v27, v24
	s_waitcnt lgkmcnt(0)
	v_pk_add_f32 v[24:25], v[24:25], v[34:35]
	ds_bpermute_b32 v35, v1, v25
	ds_bpermute_b32 v34, v1, v24
	s_waitcnt lgkmcnt(0)
	v_pk_add_f32 v[24:25], v[24:25], v[34:35]
	s_nop 0
	v_pk_fma_f32 v[24:25], v[24:25], s[22:23], v[12:13] op_sel_hi:[1,0,0]
	s_nop 0
	v_mul_f32_e32 v33, 0x4b800000, v25
	v_cmp_gt_f32_e32 vcc, s69, v25
	v_cmp_gt_f32_e64 s[0:1], s69, v24
	s_nop 0
	v_cndmask_b32_e32 v25, v25, v33, vcc
	v_rsq_f32_e32 v25, v25
	s_nop 0
	v_mul_f32_e32 v33, 0x45800000, v25
	v_cndmask_b32_e32 v34, v25, v33, vcc
	v_pk_mul_f32 v[18:19], v[18:19], v[34:35] op_sel_hi:[1,0]
	v_pk_mul_f32 v[16:17], v[16:17], v[34:35] op_sel_hi:[1,0]
	v_pk_fma_f32 v[18:19], v[2:3], v[18:19], v[6:7]
	v_pk_fma_f32 v[16:17], v[4:5], v[16:17], v[8:9]
	v_mul_f32_e32 v25, 0xbfb8aa3b, v18
	v_exp_f32_e32 v34, v25
	v_mul_f32_e32 v25, 0xbfb8aa3b, v19
	v_exp_f32_e32 v35, v25
	s_nop 0
	v_pk_add_f32 v[34:35], v[34:35], 1.0 op_sel_hi:[1,0]
	s_nop 0
	v_div_scale_f32 v25, s[20:21], v35, v35, v19
	v_rcp_f32_e32 v33, v25
	s_nop 0
	v_fma_f32 v36, -v25, v33, 1.0
	v_fmac_f32_e32 v33, v36, v33
	v_div_scale_f32 v36, vcc, v19, v35, v19
	v_mul_f32_e32 v37, v36, v33
	v_fma_f32 v38, -v25, v37, v36
	v_fmac_f32_e32 v37, v38, v33
	v_fma_f32 v25, -v25, v37, v36
	v_div_fmas_f32 v25, v25, v33, v37
	v_div_fixup_f32 v25, v25, v35, v19
	v_div_scale_f32 v19, s[20:21], v34, v34, v18
	v_rcp_f32_e32 v33, v19
	s_nop 0
	v_fma_f32 v35, -v19, v33, 1.0
	v_fmac_f32_e32 v33, v35, v33
	v_div_scale_f32 v35, vcc, v18, v34, v18
	v_mul_f32_e32 v36, v35, v33
	v_fma_f32 v37, -v19, v36, v35
	v_fmac_f32_e32 v36, v37, v33
	v_fma_f32 v19, -v19, v36, v35
	v_div_fmas_f32 v19, v19, v33, v36
	v_div_fixup_f32 v33, v19, v34, v18
	v_mul_f32_e32 v18, 0xbfb8aa3b, v16
	v_mul_f32_e32 v19, 0xbfb8aa3b, v17
	v_exp_f32_e32 v18, v18
	v_exp_f32_e32 v19, v19
	s_nop 0
	v_pk_add_f32 v[18:19], v[18:19], 1.0 op_sel_hi:[1,0]
	s_nop 0
	v_div_scale_f32 v34, s[20:21], v19, v19, v17
	v_rcp_f32_e32 v35, v34
	s_nop 0
	v_fma_f32 v36, -v34, v35, 1.0
	v_fmac_f32_e32 v35, v36, v35
	v_div_scale_f32 v36, vcc, v17, v19, v17
	v_mul_f32_e32 v37, v36, v35
	v_fma_f32 v38, -v34, v37, v36
	v_fmac_f32_e32 v37, v38, v35
	v_fma_f32 v34, -v34, v37, v36
	v_div_fmas_f32 v34, v34, v35, v37
	v_div_fixup_f32 v17, v34, v19, v17
	v_div_scale_f32 v19, s[20:21], v18, v18, v16
	v_rcp_f32_e32 v34, v19
	s_nop 0
	v_fma_f32 v35, -v19, v34, 1.0
	v_fmac_f32_e32 v34, v35, v34
	v_div_scale_f32 v35, vcc, v16, v18, v16
	v_mul_f32_e32 v36, v35, v34
	v_fma_f32 v37, -v19, v36, v35
	v_fmac_f32_e32 v36, v37, v34
	v_fma_f32 v19, -v19, v36, v35
	v_div_fmas_f32 v19, v19, v34, v36
	v_div_fixup_f32 v18, v19, v18, v16
	v_cvt_pk_bf16_f32 v16, v33, v25
	v_cvt_pk_bf16_f32 v17, v18, v17
	global_store_dwordx2 v[14:15], v[16:17], off
	v_mul_f32_e32 v14, 0x4b800000, v24
	v_cndmask_b32_e64 v14, v24, v14, s[0:1]
	v_rsq_f32_e32 v14, v14
	s_nop 0
	v_mul_f32_e32 v15, 0x45800000, v14
	v_cndmask_b32_e64 v14, v14, v15, s[0:1]
	v_pk_mul_f32 v[16:17], v[22:23], v[14:15] op_sel_hi:[1,0]
	v_pk_mul_f32 v[14:15], v[20:21], v[14:15] op_sel_hi:[1,0]
	v_pk_fma_f32 v[16:17], v[2:3], v[16:17], v[6:7]
	v_pk_fma_f32 v[14:15], v[4:5], v[14:15], v[8:9]
	v_mul_f32_e32 v18, 0xbfb8aa3b, v16
	v_mul_f32_e32 v19, 0xbfb8aa3b, v17
	v_exp_f32_e32 v18, v18
	v_exp_f32_e32 v19, v19
	s_nop 0
	v_pk_add_f32 v[18:19], v[18:19], 1.0 op_sel_hi:[1,0]
	s_nop 0
	v_div_scale_f32 v20, s[0:1], v19, v19, v17
	v_rcp_f32_e32 v21, v20
	s_nop 0
	v_fma_f32 v22, -v20, v21, 1.0
	v_fmac_f32_e32 v21, v22, v21
	v_div_scale_f32 v22, vcc, v17, v19, v17
	v_mul_f32_e32 v23, v22, v21
	v_fma_f32 v24, -v20, v23, v22
	v_fmac_f32_e32 v23, v24, v21
	v_fma_f32 v20, -v20, v23, v22
	v_div_fmas_f32 v20, v20, v21, v23
	v_div_fixup_f32 v19, v20, v19, v17
	v_div_scale_f32 v17, s[0:1], v18, v18, v16
	v_rcp_f32_e32 v20, v17
	s_nop 0
	v_fma_f32 v21, -v17, v20, 1.0
	v_fmac_f32_e32 v20, v21, v20
	v_div_scale_f32 v21, vcc, v16, v18, v16
	v_mul_f32_e32 v22, v21, v20
	v_fma_f32 v23, -v17, v22, v21
	v_fmac_f32_e32 v22, v23, v20
	v_fma_f32 v17, -v17, v22, v21
	v_div_fmas_f32 v17, v17, v20, v22
	v_div_fixup_f32 v18, v17, v18, v16
	v_mul_f32_e32 v16, 0xbfb8aa3b, v14
	v_mul_f32_e32 v17, 0xbfb8aa3b, v15
	v_exp_f32_e32 v16, v16
	v_exp_f32_e32 v17, v17
	s_nop 0
	v_pk_add_f32 v[16:17], v[16:17], 1.0 op_sel_hi:[1,0]
	s_nop 0
	v_div_scale_f32 v20, s[0:1], v17, v17, v15
	v_rcp_f32_e32 v21, v20
	s_nop 0
	v_fma_f32 v22, -v20, v21, 1.0
	v_fmac_f32_e32 v21, v22, v21
	v_div_scale_f32 v22, vcc, v15, v17, v15
	v_mul_f32_e32 v23, v22, v21
	v_fma_f32 v24, -v20, v23, v22
	v_fmac_f32_e32 v23, v24, v21
	v_fma_f32 v20, -v20, v23, v22
	v_div_fmas_f32 v20, v20, v21, v23
	v_div_fixup_f32 v15, v20, v17, v15
	v_div_scale_f32 v17, s[0:1], v16, v16, v14
	v_rcp_f32_e32 v20, v17
	s_or_b32 s0, s3, s17
	s_ashr_i32 s1, s0, 31
	s_lshl_b64 s[0:1], s[0:1], 11
	v_fma_f32 v21, -v17, v20, 1.0
	v_fmac_f32_e32 v20, v21, v20
	v_div_scale_f32 v21, vcc, v14, v16, v14
	v_mul_f32_e32 v22, v21, v20
	v_fma_f32 v23, -v17, v22, v21
	v_fmac_f32_e32 v22, v23, v20
	v_fma_f32 v17, -v17, v22, v21
	v_div_fmas_f32 v17, v17, v20, v22
	v_div_fixup_f32 v16, v17, v16, v14
	v_cvt_pk_bf16_f32 v14, v18, v19
	v_cvt_pk_bf16_f32 v15, v16, v15
	v_lshl_add_u64 v[16:17], v[10:11], 0, s[0:1]
	s_or_b32 s0, s2, 6
	global_store_dwordx2 v[16:17], v[14:15], off
	v_lshl_add_u32 v14, s0, 10, v32
	ds_read_b128 v[14:17], v14
	s_or_b32 s2, s2, 7
	s_or_b32 s0, s0, s17
	s_ashr_i32 s1, s0, 31
	s_lshl_b64 s[0:1], s[0:1], 11
	s_waitcnt lgkmcnt(0)
; DI void mixer_tile(unsigned char* smem_, const Params& p, int layer, const bf16_t* __restrict__ proj, bf16_t* __restrict__ y, int tile_) {
;     ...
;         for (int tt = 0; tt < 8; ++tt) {
;             const int t = wid * 8 + tt;
;             const f32x4 v = *(const f32x4*)(U + t * 256 + 4 * lane);
;             const float mean = wave_sum((v.x + v.y) + (v.z + v.w)) * (1.f / 256.f);
;             const float dx = v.x - mean, dy = v.y - mean, dz = v.z - mean, dw = v.w - mean;
;             const float var = wave_sum((dx * dx + dy * dy) + (dz * dz + dw * dw)) * (1.f / 256.f);
	v_mov_b32_e32 v18, v15
	v_mov_b32_e32 v19, v16
	v_mov_b32_e32 v20, v14
	v_mov_b32_e32 v21, v17
	v_pk_add_f32 v[18:19], v[18:19], v[20:21]
	s_sub_i32 s3, 14, s18
	v_add_f32_e32 v18, v18, v19
	s_waitcnt lgkmcnt(0)
	s_nop 1
	v_add_f32_dpp v18, v18, v18 quad_perm:[1,0,3,2] row_mask:0xf bank_mask:0xf
	s_nop 1
	v_add_f32_dpp v18, v18, v18 quad_perm:[2,3,0,1] row_mask:0xf bank_mask:0xf
	s_nop 1
	v_add_f32_dpp v18, v18, v18 row_half_mirror row_mask:0xf bank_mask:0xf
	s_nop 1
	v_add_f32_dpp v18, v18, v18 row_mirror row_mask:0xf bank_mask:0xf
	s_nop 1
	v_add_f32_dpp v18, v18, v18 row_bcast:15 row_mask:0xa bank_mask:0xf
	s_nop 1
	v_add_f32_dpp v18, v18, v18 row_bcast:31 row_mask:0xc bank_mask:0xf
	s_nop 0
	v_readlane_b32 vcc_lo, v18, 63
	s_nop 1
	v_mov_b32_e32 v18, vcc_lo
	v_mul_f32_e32 v18, 0x3b800000, v18
	v_pk_add_f32 v[16:17], v[16:17], v[18:19] op_sel_hi:[1,0] neg_lo:[0,1] neg_hi:[0,1]
	v_pk_add_f32 v[18:19], v[14:15], v[18:19] op_sel_hi:[1,0] neg_lo:[0,1] neg_hi:[0,1]
	v_mov_b32_e32 v21, v17
	v_mov_b32_e32 v20, v19
	v_mov_b32_e32 v14, v18
	v_mov_b32_e32 v15, v16
	v_pk_mul_f32 v[20:21], v[20:21], v[20:21]
	s_nop 0
	v_pk_fma_f32 v[24:25], v[14:15], v[14:15], v[20:21]
	v_lshl_add_u32 v20, s2, 10, v32
	ds_read_b128 v[32:35], v20
	v_lshl_add_u64 v[14:15], v[10:11], 0, s[0:1]
	s_waitcnt lgkmcnt(0)
	v_mov_b32_e32 v20, v33
	v_mov_b32_e32 v21, v34
	v_mov_b32_e32 v22, v32
	v_mov_b32_e32 v23, v35
	v_pk_add_f32 v[20:21], v[20:21], v[22:23]
	s_nop 0
	v_add_f32_e32 v20, v20, v21
	s_waitcnt lgkmcnt(0)
	s_nop 1
	v_add_f32_dpp v20, v20, v20 quad_perm:[1,0,3,2] row_mask:0xf bank_mask:0xf
	s_nop 1
	v_add_f32_dpp v20, v20, v20 quad_perm:[2,3,0,1] row_mask:0xf bank_mask:0xf
	s_nop 1
	v_add_f32_dpp v20, v20, v20 row_half_mirror row_mask:0xf bank_mask:0xf
	s_nop 1
	v_add_f32_dpp v20, v20, v20 row_mirror row_mask:0xf bank_mask:0xf
	s_nop 1
	v_add_f32_dpp v20, v20, v20 row_bcast:15 row_mask:0xa bank_mask:0xf
	s_nop 1
	v_add_f32_dpp v20, v20, v20 row_bcast:31 row_mask:0xc bank_mask:0xf
	s_nop 0
	v_readlane_b32 vcc_lo, v20, 63
	s_nop 1
	v_mov_b32_e32 v20, vcc_lo
	v_mul_f32_e32 v22, 0x3b800000, v20
	v_pk_add_f32 v[20:21], v[34:35], v[22:23] op_sel_hi:[1,0] neg_lo:[0,1] neg_hi:[0,1]
	v_pk_add_f32 v[22:23], v[32:33], v[22:23] op_sel_hi:[1,0] neg_lo:[0,1] neg_hi:[0,1]
	v_mov_b32_e32 v35, v21
	v_mov_b32_e32 v34, v23
	v_mov_b32_e32 v32, v22
	v_mov_b32_e32 v33, v20
	v_pk_mul_f32 v[34:35], v[34:35], v[34:35]
	s_nop 0
	v_pk_fma_f32 v[32:33], v[32:33], v[32:33], v[34:35]
	v_mov_b32_e32 v35, v24
	v_mov_b32_e32 v34, v32
	v_mov_b32_e32 v24, v33
	v_pk_add_f32 v[24:25], v[34:35], v[24:25]
	ds_bpermute_b32 v33, v31, v25
	ds_bpermute_b32 v32, v31, v24
	s_waitcnt lgkmcnt(0)
	v_pk_add_f32 v[24:25], v[24:25], v[32:33]
	ds_bpermute_b32 v31, v30, v25
	ds_bpermute_b32 v30, v30, v24
	s_waitcnt lgkmcnt(0)
	v_pk_add_f32 v[24:25], v[24:25], v[30:31]
	ds_bpermute_b32 v31, v29, v25
	ds_bpermute_b32 v30, v29, v24
	s_waitcnt lgkmcnt(0)
	v_pk_add_f32 v[24:25], v[24:25], v[30:31]
	ds_bpermute_b32 v29, v28, v25
	ds_bpermute_b32 v28, v28, v24
	s_waitcnt lgkmcnt(0)
	v_pk_add_f32 v[24:25], v[24:25], v[28:29]
	ds_bpermute_b32 v29, v27, v25
	ds_bpermute_b32 v28, v27, v24
	s_waitcnt lgkmcnt(0)
	v_pk_add_f32 v[24:25], v[24:25], v[28:29]
	ds_bpermute_b32 v29, v1, v25
	ds_bpermute_b32 v28, v1, v24
	s_waitcnt lgkmcnt(0)
; DI unsigned pk2(float lo, float hi) { const f32x2 v = {lo, hi}; return __builtin_bit_cast(unsigned, __builtin_convertvector(v, bf16x2_t)); }
; DI void mixer_tile(unsigned char* smem_, const Params& p, int layer, const bf16_t* __restrict__ proj, bf16_t* __restrict__ y, int tile_) {
;     ...
;             const float var = wave_sum((dx * dx + dy * dy) + (dz * dz + dw * dw)) * (1.f / 256.f);
;             const float rstd = rsqrtf(var + LN_EPS);
;             float o0 = dx * rstd * g4.x + b4.x, o1 = dy * rstd * g4.y + b4.y, o2 = dz * rstd * g4.z + b4.z, o3 = dw * rstd * g4.w + b4.w;
;             o0 = o0 / (1.f + __expf(-o0)); o1 = o1 / (1.f + __expf(-o1)); o2 = o2 / (1.f + __expf(-o2)); o3 = o3 / (1.f + __expf(-o3));
;             u32x2 wv; wv.x = pk2(o0, o1); wv.y = pk2(o2, o3);
;             *(u32x2*)(y + (size_t)(tok0 + t) * PA + 4 * lane) = wv;
;         }
;     }
;     __syncthreads();
;     ...
;         u32x4 vp[6];
; #pragma unroll
;         for (int i = 0; i < 6; ++i) {
;             const int r = 8 * i + rg, pos = pos0 - 15 + r;
;             vp[i] = (u32x4){0u, 0u, 0u, 0u};
;             if (r < 47 && pos >= 0) vp[i] = *(const u32x4*)(proj + (size_t)(tok0 - 15 + r) * DIN + 512 + 8 * ch);
	v_pk_add_f32 v[24:25], v[24:25], v[28:29]
	s_nop 0
	v_pk_fma_f32 v[12:13], v[24:25], s[22:23], v[12:13] op_sel_hi:[1,0,0]
	s_nop 0
	v_mul_f32_e32 v1, 0x4b800000, v13
	v_cmp_gt_f32_e32 vcc, s69, v13
	v_cmp_gt_f32_e64 s[0:1], s69, v12
	s_nop 0
	v_cndmask_b32_e32 v1, v13, v1, vcc
	v_rsq_f32_e32 v1, v1
	s_nop 0
	v_mul_f32_e32 v13, 0x45800000, v1
	v_cndmask_b32_e32 v24, v1, v13, vcc
	v_pk_mul_f32 v[18:19], v[18:19], v[24:25] op_sel_hi:[1,0]
	v_pk_mul_f32 v[16:17], v[16:17], v[24:25] op_sel_hi:[1,0]
	v_pk_fma_f32 v[18:19], v[2:3], v[18:19], v[6:7]
	v_pk_fma_f32 v[16:17], v[4:5], v[16:17], v[8:9]
	v_mul_f32_e32 v1, 0xbfb8aa3b, v18
	v_exp_f32_e32 v24, v1
	v_mul_f32_e32 v1, 0xbfb8aa3b, v19
	v_exp_f32_e32 v25, v1
	s_nop 0
	v_pk_add_f32 v[24:25], v[24:25], 1.0 op_sel_hi:[1,0]
	s_nop 0
	v_div_scale_f32 v1, s[20:21], v25, v25, v19
	v_rcp_f32_e32 v13, v1
	s_nop 0
	v_fma_f32 v27, -v1, v13, 1.0
	v_fmac_f32_e32 v13, v27, v13
	v_div_scale_f32 v27, vcc, v19, v25, v19
	v_mul_f32_e32 v28, v27, v13
	v_fma_f32 v29, -v1, v28, v27
	v_fmac_f32_e32 v28, v29, v13
	v_fma_f32 v1, -v1, v28, v27
	v_div_fmas_f32 v1, v1, v13, v28
	v_div_scale_f32 v13, s[20:21], v24, v24, v18
	v_div_fixup_f32 v1, v1, v25, v19
	v_rcp_f32_e32 v19, v13
	s_nop 0
	v_fma_f32 v25, -v13, v19, 1.0
	v_fmac_f32_e32 v19, v25, v19
	v_div_scale_f32 v25, vcc, v18, v24, v18
	v_mul_f32_e32 v27, v25, v19
	v_fma_f32 v28, -v13, v27, v25
	v_fmac_f32_e32 v27, v28, v19
	v_fma_f32 v13, -v13, v27, v25
	v_div_fmas_f32 v13, v13, v19, v27
	v_div_fixup_f32 v13, v13, v24, v18
	v_mul_f32_e32 v18, 0xbfb8aa3b, v16
	v_mul_f32_e32 v19, 0xbfb8aa3b, v17
	v_exp_f32_e32 v18, v18
	v_exp_f32_e32 v19, v19
	s_nop 0
	v_pk_add_f32 v[18:19], v[18:19], 1.0 op_sel_hi:[1,0]
	s_nop 0
	v_div_scale_f32 v24, s[20:21], v19, v19, v17
	v_rcp_f32_e32 v25, v24
	s_nop 0
	v_fma_f32 v27, -v24, v25, 1.0
	v_fmac_f32_e32 v25, v27, v25
	v_div_scale_f32 v27, vcc, v17, v19, v17
	v_mul_f32_e32 v28, v27, v25
	v_fma_f32 v29, -v24, v28, v27
	v_fmac_f32_e32 v28, v29, v25
	v_fma_f32 v24, -v24, v28, v27
	v_div_fmas_f32 v24, v24, v25, v28
	v_div_fixup_f32 v17, v24, v19, v17
	v_div_scale_f32 v19, s[20:21], v18, v18, v16
	v_rcp_f32_e32 v24, v19
	s_nop 0
	v_fma_f32 v25, -v19, v24, 1.0
	v_fmac_f32_e32 v24, v25, v24
	v_div_scale_f32 v25, vcc, v16, v18, v16
	v_mul_f32_e32 v27, v25, v24
	v_fma_f32 v28, -v19, v27, v25
	v_fmac_f32_e32 v27, v28, v24
	v_fma_f32 v19, -v19, v27, v25
	v_div_fmas_f32 v19, v19, v24, v27
	v_div_fixup_f32 v18, v19, v18, v16
	v_cvt_pk_bf16_f32 v16, v13, v1
	v_mul_f32_e32 v1, 0x4b800000, v12
	v_cndmask_b32_e64 v1, v12, v1, s[0:1]
	v_rsq_f32_e32 v1, v1
	v_cvt_pk_bf16_f32 v17, v18, v17
	global_store_dwordx2 v[14:15], v[16:17], off
	v_mul_f32_e32 v12, 0x45800000, v1
	v_cndmask_b32_e64 v12, v1, v12, s[0:1]
	v_pk_mul_f32 v[14:15], v[22:23], v[12:13] op_sel_hi:[1,0]
	s_nop 0
	v_pk_fma_f32 v[2:3], v[2:3], v[14:15], v[6:7]
	v_pk_mul_f32 v[6:7], v[20:21], v[12:13] op_sel_hi:[1,0]
	v_mul_f32_e32 v1, 0xbfb8aa3b, v2
	v_pk_fma_f32 v[4:5], v[4:5], v[6:7], v[8:9]
	v_exp_f32_e32 v6, v1
	v_mul_f32_e32 v1, 0xbfb8aa3b, v3
	v_exp_f32_e32 v7, v1
	v_mov_b32_e32 v14, 0
	v_mov_b32_e32 v15, 0
	v_pk_add_f32 v[6:7], v[6:7], 1.0 op_sel_hi:[1,0]
	s_nop 0
	v_div_scale_f32 v1, s[0:1], v7, v7, v3
	v_rcp_f32_e32 v8, v1
	s_nop 0
	v_fma_f32 v9, -v1, v8, 1.0
	v_fmac_f32_e32 v8, v9, v8
	v_div_scale_f32 v9, vcc, v3, v7, v3
	v_mul_f32_e32 v12, v9, v8
	v_fma_f32 v13, -v1, v12, v9
	v_fmac_f32_e32 v12, v13, v8
	v_fma_f32 v1, -v1, v12, v9
	v_div_fmas_f32 v1, v1, v8, v12
	v_div_fixup_f32 v1, v1, v7, v3
	v_div_scale_f32 v3, s[0:1], v6, v6, v2
	v_rcp_f32_e32 v7, v3
	s_nop 0
	v_fma_f32 v8, -v3, v7, 1.0
	v_fmac_f32_e32 v7, v8, v7
	v_div_scale_f32 v8, vcc, v2, v6, v2
	v_mul_f32_e32 v9, v8, v7
	v_fma_f32 v12, -v3, v9, v8
	v_fmac_f32_e32 v9, v12, v7
	v_fma_f32 v3, -v3, v9, v8
	v_div_fmas_f32 v3, v3, v7, v9
	v_div_fixup_f32 v6, v3, v6, v2
	v_mul_f32_e32 v2, 0xbfb8aa3b, v4
	v_mul_f32_e32 v3, 0xbfb8aa3b, v5
	v_exp_f32_e32 v2, v2
	v_exp_f32_e32 v3, v3
	s_nop 0
	v_pk_add_f32 v[2:3], v[2:3], 1.0 op_sel_hi:[1,0]
	s_nop 0
	v_div_scale_f32 v7, s[0:1], v3, v3, v5
	v_rcp_f32_e32 v8, v7
	s_nop 0
	v_fma_f32 v9, -v7, v8, 1.0
	v_fmac_f32_e32 v8, v9, v8
	v_div_scale_f32 v9, vcc, v5, v3, v5
	v_mul_f32_e32 v12, v9, v8
	v_fma_f32 v13, -v7, v12, v9
	v_fmac_f32_e32 v12, v13, v8
	v_fma_f32 v7, -v7, v12, v9
	v_div_fmas_f32 v7, v7, v8, v12
	v_div_fixup_f32 v3, v7, v3, v5
	v_div_scale_f32 v5, s[0:1], v2, v2, v4
	v_rcp_f32_e32 v7, v5
	s_or_b32 s0, s2, s17
	s_ashr_i32 s1, s0, 31
	s_lshl_b64 s[0:1], s[0:1], 11
	v_fma_f32 v8, -v5, v7, 1.0
	v_fmac_f32_e32 v7, v8, v7
	v_div_scale_f32 v8, vcc, v4, v2, v4
	v_mul_f32_e32 v9, v8, v7
	v_fma_f32 v12, -v5, v9, v8
	v_fmac_f32_e32 v9, v12, v7
	v_fma_f32 v5, -v5, v9, v8
	v_div_fmas_f32 v5, v5, v7, v9
	v_div_fixup_f32 v4, v5, v2, v4
	v_cvt_pk_bf16_f32 v2, v6, v1
	v_cvt_pk_bf16_f32 v3, v4, v3
	v_lshl_add_u64 v[4:5], v[10:11], 0, s[0:1]
	s_add_i32 s2, s17, -15
	v_cmp_lt_i32_e32 vcc, s3, v66
	v_mov_b32_e32 v12, 0
	v_mov_b32_e32 v13, 0
	global_store_dwordx2 v[4:5], v[2:3], off
	s_barrier
	s_and_saveexec_b64 s[0:1], vcc
	s_cbranch_execz .LBB0_172
	v_add_u32_e32 v1, s2, v66
	v_mov_b64_e32 v[2:3], s[86:87]
	v_mad_i64_i32 v[2:3], s[20:21], v1, s70, v[2:3]
	v_lshl_add_u64 v[2:3], v[2:3], 0, v[128:129]
	global_load_dwordx4 v[12:15], v[2:3], off offset:1024
